# merge K-loop unrolled (2-step prefetch, LDS writes overlapped with MFMAs); attention rescale threshold raised to 64 log2 units
# speedup vs baseline: 1.0944x; 1.0236x over previous
.Ld_loopB:
	s_and_b32 s8, s5, 1
	s_mul_i32 s4, s8, 0x4800
	s_xor_b32 s8, s8, 1
	s_mul_i32 s8, s8, 0x4800
	v_add_u32_e32 v173, s4, v255
	v_add_u32_e32 v175, s8, v169
	v_add_u32_e32 v174, s31, v168
	v_add_u32_e32 v203, s38, v168
	v_add_u32_e32 v164, s39, v169
	s_mov_b32 s19, 0
	s_mov_b32 s18, s30
	v_lshl_add_u64 v[212:213], v[134:135], 0, s[18:19]
	v_lshl_add_u64 v[220:221], v[136:137], 0, s[18:19]
	s_add_u32 s18, s30, 0x7c000
	v_lshl_add_u64 v[216:217], v[134:135], 0, s[18:19]
	v_lshl_add_u64 v[224:225], v[136:137], 0, s[18:19]
	global_load_dwordx4 v[212:215], v[212:213], off
	global_load_dwordx4 v[220:223], v[220:221], off
	global_load_dwordx4 v[216:219], v[216:217], off
	global_load_dwordx4 v[224:227], v[224:225], off
	ds_read_b128 v[228:231], v173 offset:0
	ds_read_b128 v[232:235], v173 offset:64
	ds_read_b128 v[236:239], v173 offset:4608
	ds_read_b128 v[240:243], v173 offset:4672
	v_max3_f32 v26, v88, v89, v90
	v_max3_f32 v26, v26, v91, v92
	v_max3_f32 v26, v26, v93, v94
	v_max3_f32 v26, v26, v95, v96
	v_max3_f32 v26, v26, v97, v98
	v_max3_f32 v26, v26, v99, v100
	v_max3_f32 v26, v26, v101, v102
	v_max_f32_e32 v26, v26, v103
	v_cmp_lt_f32_e32 vcc, s66, v26
	s_cbranch_vccz .Ld_nr_B_0
	v_mov_b32_e32 v27, v26
	s_nop 1
	v_permlane16_swap_b32_e32 v26, v27
	v_max_f32_e32 v26, v26, v27
	v_mov_b32_e32 v27, v26
	s_nop 1
	v_permlane32_swap_b32_e32 v26, v27
	v_max_f32_e32 v26, v26, v27
	v_cmp_lt_f32_e32 vcc, s66, v26
	s_nop 1
	v_cndmask_b32_e32 v3, 0, v26, vcc
	v_sub_f32_e32 v2, 0, v3
	v_min_f32_e32 v2, 0, v2
	v_exp_f32_e32 v2, v2
	v_sub_f32_e32 v24, v24, v3
	v_mul_f32_e32 v0, v0, v2
	v_mul_f32_e32 v28, v28, v2
	v_mul_f32_e32 v29, v29, v2
	v_mul_f32_e32 v30, v30, v2
	v_mul_f32_e32 v31, v31, v2
	v_mul_f32_e32 v32, v32, v2
	v_mul_f32_e32 v33, v33, v2
	v_mul_f32_e32 v34, v34, v2
	v_mul_f32_e32 v35, v35, v2
	v_mul_f32_e32 v40, v40, v2
	v_mul_f32_e32 v41, v41, v2
	v_mul_f32_e32 v42, v42, v2
	v_mul_f32_e32 v43, v43, v2
	v_mul_f32_e32 v52, v52, v2
	v_mul_f32_e32 v53, v53, v2
	v_mul_f32_e32 v54, v54, v2
	v_mul_f32_e32 v55, v55, v2
	v_mul_f32_e32 v56, v56, v2
	v_mul_f32_e32 v57, v57, v2
	v_mul_f32_e32 v58, v58, v2
	v_mul_f32_e32 v59, v59, v2
	v_mul_f32_e32 v64, v64, v2
	v_mul_f32_e32 v65, v65, v2
	v_mul_f32_e32 v66, v66, v2
	v_mul_f32_e32 v67, v67, v2
	v_mul_f32_e32 v72, v72, v2
	v_mul_f32_e32 v73, v73, v2
	v_mul_f32_e32 v74, v74, v2
	v_mul_f32_e32 v75, v75, v2
	v_mul_f32_e32 v84, v84, v2
	v_mul_f32_e32 v85, v85, v2
	v_mul_f32_e32 v86, v86, v2
	v_mul_f32_e32 v87, v87, v2
	v_sub_f32_e32 v88, v88, v3
	v_sub_f32_e32 v89, v89, v3
	v_sub_f32_e32 v90, v90, v3
	v_sub_f32_e32 v91, v91, v3
	v_sub_f32_e32 v92, v92, v3
	v_sub_f32_e32 v93, v93, v3
	v_sub_f32_e32 v94, v94, v3
	v_sub_f32_e32 v95, v95, v3
	v_sub_f32_e32 v96, v96, v3
	v_sub_f32_e32 v97, v97, v3
	v_sub_f32_e32 v98, v98, v3
	v_sub_f32_e32 v99, v99, v3
	v_sub_f32_e32 v100, v100, v3
	v_sub_f32_e32 v101, v101, v3
	v_sub_f32_e32 v102, v102, v3
	v_sub_f32_e32 v103, v103, v3
.Ld_nr_B_0:
	v_exp_f32_e32 v88, v88
	v_exp_f32_e32 v89, v89
	v_exp_f32_e32 v90, v90
	v_exp_f32_e32 v91, v91
	v_exp_f32_e32 v92, v92
	v_exp_f32_e32 v93, v93
	v_exp_f32_e32 v94, v94
	v_exp_f32_e32 v95, v95
	v_exp_f32_e32 v96, v96
	v_exp_f32_e32 v97, v97
	v_exp_f32_e32 v98, v98
	v_exp_f32_e32 v99, v99
	v_exp_f32_e32 v100, v100
	v_exp_f32_e32 v101, v101
	v_exp_f32_e32 v102, v102
	v_exp_f32_e32 v103, v103
	s_nop 0
	v_add_f32_e32 v26, v88, v89
	v_add_f32_e32 v26, v26, v90
	v_add_f32_e32 v26, v26, v91
	v_add_f32_e32 v26, v26, v92
	v_add_f32_e32 v26, v26, v93
	v_add_f32_e32 v26, v26, v94
	v_add_f32_e32 v26, v26, v95
	v_add_f32_e32 v26, v26, v96
	v_add_f32_e32 v26, v26, v97
	v_add_f32_e32 v26, v26, v98
	v_add_f32_e32 v26, v26, v99
	v_add_f32_e32 v26, v26, v100
	v_add_f32_e32 v26, v26, v101
	v_add_f32_e32 v26, v26, v102
	v_add_f32_e32 v26, v26, v103
	v_add_f32_e32 v0, v0, v26
	v_cvt_pk_bf16_f32 v120, v88, v89
	v_cvt_pk_bf16_f32 v121, v90, v91
	v_cvt_pk_bf16_f32 v122, v92, v93
	v_cvt_pk_bf16_f32 v123, v94, v95
	v_cvt_pk_bf16_f32 v124, v96, v97
	v_cvt_pk_bf16_f32 v125, v98, v99
	v_cvt_pk_bf16_f32 v126, v100, v101
	v_cvt_pk_bf16_f32 v127, v102, v103
	v_max3_f32 v26, v104, v105, v106
	v_max3_f32 v26, v26, v107, v108
	v_max3_f32 v26, v26, v109, v110
	v_max3_f32 v26, v26, v111, v112
	v_max3_f32 v26, v26, v113, v114
	v_max3_f32 v26, v26, v115, v116
	v_max3_f32 v26, v26, v117, v118
	v_max_f32_e32 v26, v26, v119
	v_cmp_lt_f32_e32 vcc, s66, v26
	s_cbranch_vccz .Ld_nr_B_1
	v_mov_b32_e32 v27, v26
	s_nop 1
	v_permlane16_swap_b32_e32 v26, v27
	v_max_f32_e32 v26, v26, v27
	v_mov_b32_e32 v27, v26
	s_nop 1
	v_permlane32_swap_b32_e32 v26, v27
	v_max_f32_e32 v26, v26, v27
	v_cmp_lt_f32_e32 vcc, s66, v26
	s_nop 1
	v_cndmask_b32_e32 v3, 0, v26, vcc
	v_sub_f32_e32 v2, 0, v3
	v_min_f32_e32 v2, 0, v2
	v_exp_f32_e32 v2, v2
	v_sub_f32_e32 v25, v25, v3
	v_mul_f32_e32 v151, v151, v2
	v_mul_f32_e32 v36, v36, v2
	v_mul_f32_e32 v37, v37, v2
	v_mul_f32_e32 v38, v38, v2
	v_mul_f32_e32 v39, v39, v2
	v_mul_f32_e32 v44, v44, v2
	v_mul_f32_e32 v45, v45, v2
	v_mul_f32_e32 v46, v46, v2
	v_mul_f32_e32 v47, v47, v2
	v_mul_f32_e32 v48, v48, v2
	v_mul_f32_e32 v49, v49, v2
	v_mul_f32_e32 v50, v50, v2
	v_mul_f32_e32 v51, v51, v2
	v_mul_f32_e32 v60, v60, v2
	v_mul_f32_e32 v61, v61, v2
	v_mul_f32_e32 v62, v62, v2
	v_mul_f32_e32 v63, v63, v2
	v_mul_f32_e32 v68, v68, v2
	v_mul_f32_e32 v69, v69, v2
	v_mul_f32_e32 v70, v70, v2
	v_mul_f32_e32 v71, v71, v2
	v_mul_f32_e32 v76, v76, v2
	v_mul_f32_e32 v77, v77, v2
	v_mul_f32_e32 v78, v78, v2
	v_mul_f32_e32 v79, v79, v2
	v_mul_f32_e32 v80, v80, v2
	v_mul_f32_e32 v81, v81, v2
	v_mul_f32_e32 v82, v82, v2
	v_mul_f32_e32 v83, v83, v2
	v_mul_f32_e32 v20, v20, v2
	v_mul_f32_e32 v21, v21, v2
	v_mul_f32_e32 v22, v22, v2
	v_mul_f32_e32 v23, v23, v2
	v_sub_f32_e32 v104, v104, v3
	v_sub_f32_e32 v105, v105, v3
	v_sub_f32_e32 v106, v106, v3
	v_sub_f32_e32 v107, v107, v3
	v_sub_f32_e32 v108, v108, v3
	v_sub_f32_e32 v109, v109, v3
	v_sub_f32_e32 v110, v110, v3
	v_sub_f32_e32 v111, v111, v3
	v_sub_f32_e32 v112, v112, v3
	v_sub_f32_e32 v113, v113, v3
	v_sub_f32_e32 v114, v114, v3
	v_sub_f32_e32 v115, v115, v3
	v_sub_f32_e32 v116, v116, v3
	v_sub_f32_e32 v117, v117, v3
	v_sub_f32_e32 v118, v118, v3
	v_sub_f32_e32 v119, v119, v3
.Ld_nr_B_1:
	v_exp_f32_e32 v104, v104
	v_exp_f32_e32 v105, v105
	v_exp_f32_e32 v106, v106
	v_exp_f32_e32 v107, v107
	v_exp_f32_e32 v108, v108
	v_exp_f32_e32 v109, v109
	v_exp_f32_e32 v110, v110
	v_exp_f32_e32 v111, v111
	v_exp_f32_e32 v112, v112
	v_exp_f32_e32 v113, v113
	v_exp_f32_e32 v114, v114
	v_exp_f32_e32 v115, v115
	v_exp_f32_e32 v116, v116
	v_exp_f32_e32 v117, v117
	v_exp_f32_e32 v118, v118
	v_exp_f32_e32 v119, v119
	s_nop 0
	v_add_f32_e32 v26, v104, v105
	v_add_f32_e32 v26, v26, v106
	v_add_f32_e32 v26, v26, v107
	v_add_f32_e32 v26, v26, v108
	v_add_f32_e32 v26, v26, v109
	v_add_f32_e32 v26, v26, v110
	v_add_f32_e32 v26, v26, v111
	v_add_f32_e32 v26, v26, v112
	v_add_f32_e32 v26, v26, v113
	v_add_f32_e32 v26, v26, v114
	v_add_f32_e32 v26, v26, v115
	v_add_f32_e32 v26, v26, v116
	v_add_f32_e32 v26, v26, v117
	v_add_f32_e32 v26, v26, v118
	v_add_f32_e32 v26, v26, v119
	v_add_f32_e32 v151, v151, v26
	v_cvt_pk_bf16_f32 v128, v104, v105
	v_cvt_pk_bf16_f32 v129, v106, v107
	v_cvt_pk_bf16_f32 v130, v108, v109
	v_cvt_pk_bf16_f32 v131, v110, v111
	v_cvt_pk_bf16_f32 v152, v112, v113
	v_cvt_pk_bf16_f32 v153, v114, v115
	v_cvt_pk_bf16_f32 v154, v116, v117
	v_cvt_pk_bf16_f32 v155, v118, v119
	v_mov_b32_e32 v156, v165
	v_add_f32_e32 v157, 0x3f800000, v165
	v_add_f32_e32 v158, 0x40000000, v165
	v_add_f32_e32 v159, 0x40400000, v165
	v_add_f32_e32 v160, 0x41800000, v165
	v_add_f32_e32 v161, 0x41880000, v165
	v_add_f32_e32 v162, 0x41900000, v165
	v_add_f32_e32 v163, 0x41980000, v165
	v_add_f32_e32 v176, 0x42000000, v165
	v_add_f32_e32 v177, 0x42040000, v165
	v_add_f32_e32 v178, 0x42080000, v165
	v_add_f32_e32 v179, 0x420c0000, v165
	v_add_f32_e32 v180, 0x42400000, v165
	v_add_f32_e32 v181, 0x42440000, v165
	v_add_f32_e32 v182, 0x42480000, v165
	v_add_f32_e32 v183, 0x424c0000, v165
	v_fma_f32 v204, -v150, |v156|, v25
	v_fma_f32 v205, -v150, |v157|, v25
	v_fma_f32 v206, -v150, |v158|, v25
	v_fma_f32 v207, -v150, |v159|, v25
	v_fma_f32 v208, -v150, |v160|, v25
	v_fma_f32 v209, -v150, |v161|, v25
	v_fma_f32 v210, -v150, |v162|, v25
	v_fma_f32 v211, -v150, |v163|, v25
	v_fma_f32 v184, -v150, |v176|, v25
	v_fma_f32 v185, -v150, |v177|, v25
	v_fma_f32 v186, -v150, |v178|, v25
	v_fma_f32 v187, -v150, |v179|, v25
	v_fma_f32 v188, -v150, |v180|, v25
	v_fma_f32 v189, -v150, |v181|, v25
	v_fma_f32 v190, -v150, |v182|, v25
	v_fma_f32 v191, -v150, |v183|, v25
	v_fma_f32 v156, -v150, |v156|, v24
	v_fma_f32 v157, -v150, |v157|, v24
	v_fma_f32 v158, -v150, |v158|, v24
	v_fma_f32 v159, -v150, |v159|, v24
	v_fma_f32 v160, -v150, |v160|, v24
	v_fma_f32 v161, -v150, |v161|, v24
	v_fma_f32 v162, -v150, |v162|, v24
	v_fma_f32 v163, -v150, |v163|, v24
	v_fma_f32 v176, -v150, |v176|, v24
	v_fma_f32 v177, -v150, |v177|, v24
	v_fma_f32 v178, -v150, |v178|, v24
	v_fma_f32 v179, -v150, |v179|, v24
	v_fma_f32 v180, -v150, |v180|, v24
	v_fma_f32 v181, -v150, |v181|, v24
	v_fma_f32 v182, -v150, |v182|, v24
	v_fma_f32 v183, -v150, |v183|, v24
	ds_read_b128 v[244:247], v173 offset:9216
	s_waitcnt lgkmcnt(4)
	v_mfma_f32_16x16x32_bf16 v[88:91], v[228:231], v[4:7], v[156:159]
	ds_read_b128 v[248:251], v173 offset:9280
	s_waitcnt lgkmcnt(4)
	v_mfma_f32_16x16x32_bf16 v[88:91], v[232:235], v[8:11], v[88:91]
	ds_read_b128 v[228:231], v173 offset:13824
	s_waitcnt lgkmcnt(4)
	v_mfma_f32_16x16x32_bf16 v[92:95], v[236:239], v[4:7], v[160:163]
	ds_read_b128 v[232:235], v173 offset:13888
	s_waitcnt lgkmcnt(4)
	v_mfma_f32_16x16x32_bf16 v[92:95], v[240:243], v[8:11], v[92:95]
	ds_read_b128 v[236:239], v173 offset:128
	s_waitcnt lgkmcnt(4)
	v_mfma_f32_16x16x32_bf16 v[96:99], v[244:247], v[4:7], v[176:179]
	ds_read_b128 v[240:243], v173 offset:192
	s_waitcnt lgkmcnt(4)
	v_mfma_f32_16x16x32_bf16 v[96:99], v[248:251], v[8:11], v[96:99]
	ds_read_b128 v[244:247], v173 offset:4736
	s_waitcnt lgkmcnt(4)
	v_mfma_f32_16x16x32_bf16 v[100:103], v[228:231], v[4:7], v[180:183]
	ds_read_b128 v[248:251], v173 offset:4800
	s_waitcnt lgkmcnt(4)
	v_mfma_f32_16x16x32_bf16 v[100:103], v[232:235], v[8:11], v[100:103]
	ds_read_b128 v[228:231], v173 offset:9344
	s_waitcnt lgkmcnt(4)
	v_mfma_f32_16x16x32_bf16 v[104:107], v[236:239], v[12:15], v[204:207]
	ds_read_b128 v[232:235], v173 offset:9408
	s_waitcnt lgkmcnt(4)
	v_mfma_f32_16x16x32_bf16 v[104:107], v[240:243], v[16:19], v[104:107]
	ds_read_b128 v[236:239], v173 offset:13952
	s_waitcnt lgkmcnt(4)
	v_mfma_f32_16x16x32_bf16 v[108:111], v[244:247], v[12:15], v[208:211]
	ds_read_b128 v[240:243], v173 offset:14016
	s_waitcnt lgkmcnt(4)
	v_mfma_f32_16x16x32_bf16 v[108:111], v[248:251], v[16:19], v[108:111]
	ds_read_b64_tr_b16 v[244:245], v174 offset:36864
	ds_read_b64_tr_b16 v[246:247], v174 offset:41472
	s_waitcnt lgkmcnt(5)
	v_mfma_f32_16x16x32_bf16 v[112:115], v[228:231], v[12:15], v[184:187]
	ds_read_b64_tr_b16 v[248:249], v174 offset:36896
	ds_read_b64_tr_b16 v[250:251], v174 offset:41504
	s_waitcnt lgkmcnt(6)
	v_mfma_f32_16x16x32_bf16 v[112:115], v[232:235], v[16:19], v[112:115]
	ds_read_b64_tr_b16 v[228:229], v174 offset:36928
	ds_read_b64_tr_b16 v[230:231], v174 offset:41536
	s_waitcnt lgkmcnt(7)
	v_mfma_f32_16x16x32_bf16 v[116:119], v[236:239], v[12:15], v[188:191]
	ds_read_b64_tr_b16 v[232:233], v174 offset:36960
	ds_read_b64_tr_b16 v[234:235], v174 offset:41568
	s_waitcnt lgkmcnt(8)
	v_mfma_f32_16x16x32_bf16 v[116:119], v[240:243], v[16:19], v[116:119]
	ds_read_b64_tr_b16 v[236:237], v174 offset:36992
	ds_read_b64_tr_b16 v[238:239], v174 offset:41600
	s_waitcnt lgkmcnt(8)
	v_mfma_f32_16x16x32_bf16 v[28:31], v[244:247], v[120:123], v[28:31]
	v_mfma_f32_16x16x32_bf16 v[36:39], v[244:247], v[128:131], v[36:39]
	ds_read_b64_tr_b16 v[240:241], v174 offset:37024
	ds_read_b64_tr_b16 v[242:243], v174 offset:41632
	s_waitcnt lgkmcnt(8)
	v_mfma_f32_16x16x32_bf16 v[32:35], v[248:251], v[120:123], v[32:35]
	v_mfma_f32_16x16x32_bf16 v[44:47], v[248:251], v[128:131], v[44:47]
	ds_read_b64_tr_b16 v[244:245], v174 offset:37056
	ds_read_b64_tr_b16 v[246:247], v174 offset:41664
	s_waitcnt lgkmcnt(8)
	v_mfma_f32_16x16x32_bf16 v[40:43], v[228:231], v[120:123], v[40:43]
	v_mfma_f32_16x16x32_bf16 v[48:51], v[228:231], v[128:131], v[48:51]
	ds_read_b64_tr_b16 v[248:249], v174 offset:37088
	ds_read_b64_tr_b16 v[250:251], v174 offset:41696
	s_waitcnt lgkmcnt(8)
	v_mfma_f32_16x16x32_bf16 v[52:55], v[232:235], v[120:123], v[52:55]
	v_mfma_f32_16x16x32_bf16 v[60:63], v[232:235], v[128:131], v[60:63]
	ds_read_b64_tr_b16 v[228:229], v174 offset:46080
	ds_read_b64_tr_b16 v[230:231], v174 offset:50688
	s_waitcnt lgkmcnt(8)
	v_mfma_f32_16x16x32_bf16 v[56:59], v[236:239], v[120:123], v[56:59]
	v_mfma_f32_16x16x32_bf16 v[68:71], v[236:239], v[128:131], v[68:71]
	ds_read_b64_tr_b16 v[232:233], v174 offset:46112
	ds_read_b64_tr_b16 v[234:235], v174 offset:50720
	s_waitcnt lgkmcnt(8)
	v_mfma_f32_16x16x32_bf16 v[64:67], v[240:243], v[120:123], v[64:67]
	v_mfma_f32_16x16x32_bf16 v[76:79], v[240:243], v[128:131], v[76:79]
	ds_read_b64_tr_b16 v[236:237], v174 offset:46144
	ds_read_b64_tr_b16 v[238:239], v174 offset:50752
	s_waitcnt lgkmcnt(8)
	v_mfma_f32_16x16x32_bf16 v[72:75], v[244:247], v[120:123], v[72:75]
	v_mfma_f32_16x16x32_bf16 v[80:83], v[244:247], v[128:131], v[80:83]
	ds_read_b64_tr_b16 v[240:241], v174 offset:46176
	ds_read_b64_tr_b16 v[242:243], v174 offset:50784
	s_waitcnt lgkmcnt(8)
	v_mfma_f32_16x16x32_bf16 v[84:87], v[248:251], v[120:123], v[84:87]
	v_mfma_f32_16x16x32_bf16 v[20:23], v[248:251], v[128:131], v[20:23]
	ds_read_b64_tr_b16 v[244:245], v174 offset:46208
	ds_read_b64_tr_b16 v[246:247], v174 offset:50816
	s_waitcnt lgkmcnt(8)
	v_mfma_f32_16x16x32_bf16 v[28:31], v[228:231], v[124:127], v[28:31]
	v_mfma_f32_16x16x32_bf16 v[36:39], v[228:231], v[152:155], v[36:39]
	ds_read_b64_tr_b16 v[248:249], v174 offset:46240
	ds_read_b64_tr_b16 v[250:251], v174 offset:50848
	s_waitcnt lgkmcnt(8)
	v_mfma_f32_16x16x32_bf16 v[32:35], v[232:235], v[124:127], v[32:35]
	v_mfma_f32_16x16x32_bf16 v[44:47], v[232:235], v[152:155], v[44:47]
	ds_read_b64_tr_b16 v[228:229], v174 offset:46272
	ds_read_b64_tr_b16 v[230:231], v174 offset:50880
	s_waitcnt lgkmcnt(8)
	v_mfma_f32_16x16x32_bf16 v[40:43], v[236:239], v[124:127], v[40:43]
	v_mfma_f32_16x16x32_bf16 v[48:51], v[236:239], v[152:155], v[48:51]
	ds_read_b64_tr_b16 v[232:233], v174 offset:46304
	ds_read_b64_tr_b16 v[234:235], v174 offset:50912
	s_waitcnt lgkmcnt(8)
	v_mfma_f32_16x16x32_bf16 v[52:55], v[240:243], v[124:127], v[52:55]
	v_mfma_f32_16x16x32_bf16 v[60:63], v[240:243], v[152:155], v[60:63]
	s_waitcnt lgkmcnt(6)
	v_mfma_f32_16x16x32_bf16 v[56:59], v[244:247], v[124:127], v[56:59]
	v_mfma_f32_16x16x32_bf16 v[68:71], v[244:247], v[152:155], v[68:71]
	s_waitcnt lgkmcnt(4)
	v_mfma_f32_16x16x32_bf16 v[64:67], v[248:251], v[124:127], v[64:67]
	v_mfma_f32_16x16x32_bf16 v[76:79], v[248:251], v[152:155], v[76:79]
	s_waitcnt lgkmcnt(2)
	v_mfma_f32_16x16x32_bf16 v[72:75], v[228:231], v[124:127], v[72:75]
	v_mfma_f32_16x16x32_bf16 v[80:83], v[228:231], v[152:155], v[80:83]
	s_waitcnt lgkmcnt(0)
	v_mfma_f32_16x16x32_bf16 v[84:87], v[232:235], v[124:127], v[84:87]
	v_mfma_f32_16x16x32_bf16 v[20:23], v[232:235], v[152:155], v[20:23]
	s_waitcnt vmcnt(0)
	ds_write_b128 v175, v[212:215]
	ds_write_b128 v175, v[216:219] offset:9216
	ds_write_b128 v164, v[220:223] offset:36864
	ds_write_b128 v164, v[224:227] offset:46080
	s_mov_b32 s31, s38
	s_mov_b32 s38, s39
	s_add_i32 s39, s39, 0x4800
	s_cmp_lg_u32 s39, 0xd800
	s_cselect_b32 s39, s39, 0
	s_mov_b32 s66, 0xff800000
	s_cmp_ge_u32 s5, 1
	s_cselect_b32 s66, 0x42800000, s66
	s_add_i32 s5, s5, 1
	s_min_u32 s8, s5, 62
	s_add_i32 s8, s8, 1
	s_mul_i32 s30, s8, 0xf8000
	v_add_f32_e32 v165, 0x42800000, v165
	s_waitcnt lgkmcnt(0)
	s_barrier
	s_cmp_lt_u32 s5, 64
	s_cbranch_scc1 .Ld_loopB
	v_add_u32_e32 v174, s31, v168
	ds_read_b64_tr_b16 v[228:229], v174 offset:36864
	ds_read_b64_tr_b16 v[230:231], v174 offset:41472
	ds_read_b64_tr_b16 v[232:233], v174 offset:36896
	ds_read_b64_tr_b16 v[234:235], v174 offset:41504
	ds_read_b64_tr_b16 v[236:237], v174 offset:36928
	ds_read_b64_tr_b16 v[238:239], v174 offset:41536
	ds_read_b64_tr_b16 v[240:241], v174 offset:36960
	ds_read_b64_tr_b16 v[242:243], v174 offset:41568
	v_max3_f32 v26, v88, v89, v90
	v_max3_f32 v26, v26, v91, v92
	v_max3_f32 v26, v26, v93, v94
	v_max3_f32 v26, v26, v95, v96
	v_max3_f32 v26, v26, v97, v98
	v_max3_f32 v26, v26, v99, v100
	v_max3_f32 v26, v26, v101, v102
	v_max_f32_e32 v26, v26, v103
	v_cmp_lt_f32_e32 vcc, s66, v26
	s_cbranch_vccz .Ld_nr_Bt_0
	v_mov_b32_e32 v27, v26
	s_nop 1
	v_permlane16_swap_b32_e32 v26, v27
	v_max_f32_e32 v26, v26, v27
	v_mov_b32_e32 v27, v26
	s_nop 1
	v_permlane32_swap_b32_e32 v26, v27
	v_max_f32_e32 v26, v26, v27
	v_cmp_lt_f32_e32 vcc, s66, v26
	s_nop 1
	v_cndmask_b32_e32 v3, 0, v26, vcc
	v_sub_f32_e32 v2, 0, v3
	v_min_f32_e32 v2, 0, v2
	v_exp_f32_e32 v2, v2
	v_sub_f32_e32 v24, v24, v3
	v_mul_f32_e32 v0, v0, v2
	v_mul_f32_e32 v28, v28, v2
	v_mul_f32_e32 v29, v29, v2
	v_mul_f32_e32 v30, v30, v2
	v_mul_f32_e32 v31, v31, v2
	v_mul_f32_e32 v32, v32, v2
	v_mul_f32_e32 v33, v33, v2
	v_mul_f32_e32 v34, v34, v2
	v_mul_f32_e32 v35, v35, v2
	v_mul_f32_e32 v40, v40, v2
	v_mul_f32_e32 v41, v41, v2
	v_mul_f32_e32 v42, v42, v2
	v_mul_f32_e32 v43, v43, v2
	v_mul_f32_e32 v52, v52, v2
	v_mul_f32_e32 v53, v53, v2
	v_mul_f32_e32 v54, v54, v2
	v_mul_f32_e32 v55, v55, v2
	v_mul_f32_e32 v56, v56, v2
	v_mul_f32_e32 v57, v57, v2
	v_mul_f32_e32 v58, v58, v2
	v_mul_f32_e32 v59, v59, v2
	v_mul_f32_e32 v64, v64, v2
	v_mul_f32_e32 v65, v65, v2
	v_mul_f32_e32 v66, v66, v2
	v_mul_f32_e32 v67, v67, v2
	v_mul_f32_e32 v72, v72, v2
	v_mul_f32_e32 v73, v73, v2
	v_mul_f32_e32 v74, v74, v2
	v_mul_f32_e32 v75, v75, v2
	v_mul_f32_e32 v84, v84, v2
	v_mul_f32_e32 v85, v85, v2
	v_mul_f32_e32 v86, v86, v2
	v_mul_f32_e32 v87, v87, v2
	v_sub_f32_e32 v88, v88, v3
	v_sub_f32_e32 v89, v89, v3
	v_sub_f32_e32 v90, v90, v3
	v_sub_f32_e32 v91, v91, v3
	v_sub_f32_e32 v92, v92, v3
	v_sub_f32_e32 v93, v93, v3
	v_sub_f32_e32 v94, v94, v3
	v_sub_f32_e32 v95, v95, v3
	v_sub_f32_e32 v96, v96, v3
	v_sub_f32_e32 v97, v97, v3
	v_sub_f32_e32 v98, v98, v3
	v_sub_f32_e32 v99, v99, v3
	v_sub_f32_e32 v100, v100, v3
	v_sub_f32_e32 v101, v101, v3
	v_sub_f32_e32 v102, v102, v3
	v_sub_f32_e32 v103, v103, v3

.Ld_loopA:
	s_and_b32 s8, s5, 1
	s_mul_i32 s4, s8, 0x4800
	s_xor_b32 s8, s8, 1
	s_mul_i32 s8, s8, 0x4800
	v_add_u32_e32 v173, s4, v255
	v_add_u32_e32 v175, s8, v169
	v_add_u32_e32 v174, s31, v168
	v_add_u32_e32 v203, s38, v168
	v_add_u32_e32 v164, s39, v169
	s_mov_b32 s19, 0
	s_mov_b32 s18, s30
	v_lshl_add_u64 v[212:213], v[134:135], 0, s[18:19]
	v_lshl_add_u64 v[220:221], v[136:137], 0, s[18:19]
	s_add_u32 s18, s30, 0x7c000
	v_lshl_add_u64 v[216:217], v[134:135], 0, s[18:19]
	v_lshl_add_u64 v[224:225], v[136:137], 0, s[18:19]
	global_load_dwordx4 v[212:215], v[212:213], off
	global_load_dwordx4 v[220:223], v[220:221], off
	global_load_dwordx4 v[216:219], v[216:217], off
	global_load_dwordx4 v[224:227], v[224:225], off
	ds_read_b64_tr_b16 v[228:229], v174 offset:36864
	ds_read_b64_tr_b16 v[230:231], v174 offset:41472
	ds_read_b64_tr_b16 v[232:233], v174 offset:36896
	ds_read_b64_tr_b16 v[234:235], v174 offset:41504
	ds_read_b64_tr_b16 v[236:237], v174 offset:36928
	ds_read_b64_tr_b16 v[238:239], v174 offset:41536
	ds_read_b64_tr_b16 v[240:241], v174 offset:36960
	ds_read_b64_tr_b16 v[242:243], v174 offset:41568
	ds_read_b64_tr_b16 v[244:245], v174 offset:36992
	ds_read_b64_tr_b16 v[246:247], v174 offset:41600
	s_waitcnt lgkmcnt(8)
	v_mfma_f32_16x16x32_bf16 v[28:31], v[228:231], v[120:123], v[28:31]
	v_mfma_f32_16x16x32_bf16 v[36:39], v[228:231], v[128:131], v[36:39]
	ds_read_b64_tr_b16 v[248:249], v174 offset:37024
	ds_read_b64_tr_b16 v[250:251], v174 offset:41632
	s_waitcnt lgkmcnt(8)
	v_mfma_f32_16x16x32_bf16 v[32:35], v[232:235], v[120:123], v[32:35]
	v_mfma_f32_16x16x32_bf16 v[44:47], v[232:235], v[128:131], v[44:47]
	ds_read_b64_tr_b16 v[228:229], v174 offset:37056
	ds_read_b64_tr_b16 v[230:231], v174 offset:41664
	s_waitcnt lgkmcnt(8)
	v_mfma_f32_16x16x32_bf16 v[40:43], v[236:239], v[120:123], v[40:43]
	v_mfma_f32_16x16x32_bf16 v[48:51], v[236:239], v[128:131], v[48:51]
	ds_read_b64_tr_b16 v[232:233], v174 offset:37088
	ds_read_b64_tr_b16 v[234:235], v174 offset:41696
	s_waitcnt lgkmcnt(8)
	v_mfma_f32_16x16x32_bf16 v[52:55], v[240:243], v[120:123], v[52:55]
	v_mfma_f32_16x16x32_bf16 v[60:63], v[240:243], v[128:131], v[60:63]
	ds_read_b64_tr_b16 v[236:237], v174 offset:46080
	ds_read_b64_tr_b16 v[238:239], v174 offset:50688
	s_waitcnt lgkmcnt(8)
	v_mfma_f32_16x16x32_bf16 v[56:59], v[244:247], v[120:123], v[56:59]
	v_mfma_f32_16x16x32_bf16 v[68:71], v[244:247], v[128:131], v[68:71]
	ds_read_b64_tr_b16 v[240:241], v174 offset:46112
	ds_read_b64_tr_b16 v[242:243], v174 offset:50720
	s_waitcnt lgkmcnt(8)
	v_mfma_f32_16x16x32_bf16 v[64:67], v[248:251], v[120:123], v[64:67]
	v_mfma_f32_16x16x32_bf16 v[76:79], v[248:251], v[128:131], v[76:79]
	ds_read_b64_tr_b16 v[244:245], v174 offset:46144
	ds_read_b64_tr_b16 v[246:247], v174 offset:50752
	s_waitcnt lgkmcnt(8)
	v_mfma_f32_16x16x32_bf16 v[72:75], v[228:231], v[120:123], v[72:75]
	v_mfma_f32_16x16x32_bf16 v[80:83], v[228:231], v[128:131], v[80:83]
	ds_read_b64_tr_b16 v[248:249], v174 offset:46176
	ds_read_b64_tr_b16 v[250:251], v174 offset:50784
	s_waitcnt lgkmcnt(8)
	v_mfma_f32_16x16x32_bf16 v[84:87], v[232:235], v[120:123], v[84:87]
	v_mfma_f32_16x16x32_bf16 v[20:23], v[232:235], v[128:131], v[20:23]
	ds_read_b64_tr_b16 v[228:229], v174 offset:46208
	ds_read_b64_tr_b16 v[230:231], v174 offset:50816
	s_waitcnt lgkmcnt(8)
	v_mfma_f32_16x16x32_bf16 v[28:31], v[236:239], v[124:127], v[28:31]
	v_mfma_f32_16x16x32_bf16 v[36:39], v[236:239], v[152:155], v[36:39]
	ds_read_b64_tr_b16 v[232:233], v174 offset:46240
	ds_read_b64_tr_b16 v[234:235], v174 offset:50848
	s_waitcnt lgkmcnt(8)
	v_mfma_f32_16x16x32_bf16 v[32:35], v[240:243], v[124:127], v[32:35]
	v_mfma_f32_16x16x32_bf16 v[44:47], v[240:243], v[152:155], v[44:47]
	ds_read_b64_tr_b16 v[236:237], v174 offset:46272
	ds_read_b64_tr_b16 v[238:239], v174 offset:50880
	s_waitcnt lgkmcnt(8)
	v_mfma_f32_16x16x32_bf16 v[40:43], v[244:247], v[124:127], v[40:43]
	v_mfma_f32_16x16x32_bf16 v[48:51], v[244:247], v[152:155], v[48:51]
	ds_read_b64_tr_b16 v[240:241], v174 offset:46304
	ds_read_b64_tr_b16 v[242:243], v174 offset:50912
	s_waitcnt lgkmcnt(8)
	v_mfma_f32_16x16x32_bf16 v[52:55], v[248:251], v[124:127], v[52:55]
	v_mfma_f32_16x16x32_bf16 v[60:63], v[248:251], v[152:155], v[60:63]
	ds_read_b128 v[244:247], v173 offset:0
	s_waitcnt lgkmcnt(7)
	v_mfma_f32_16x16x32_bf16 v[56:59], v[228:231], v[124:127], v[56:59]
	v_mfma_f32_16x16x32_bf16 v[68:71], v[228:231], v[152:155], v[68:71]
	ds_read_b128 v[248:251], v173 offset:64
	s_waitcnt lgkmcnt(6)
	v_mfma_f32_16x16x32_bf16 v[64:67], v[232:235], v[124:127], v[64:67]
	v_mfma_f32_16x16x32_bf16 v[76:79], v[232:235], v[152:155], v[76:79]
	ds_read_b128 v[228:231], v173 offset:4608
	s_waitcnt lgkmcnt(5)
	v_mfma_f32_16x16x32_bf16 v[72:75], v[236:239], v[124:127], v[72:75]
	v_mfma_f32_16x16x32_bf16 v[80:83], v[236:239], v[152:155], v[80:83]
	ds_read_b128 v[232:235], v173 offset:4672
	s_waitcnt lgkmcnt(4)
	v_mfma_f32_16x16x32_bf16 v[84:87], v[240:243], v[124:127], v[84:87]
	v_mfma_f32_16x16x32_bf16 v[20:23], v[240:243], v[152:155], v[20:23]
	ds_read_b128 v[236:239], v173 offset:9216
	s_waitcnt lgkmcnt(4)
	v_mfma_f32_16x16x32_bf16 v[88:91], v[244:247], v[4:7], v[156:159]
	ds_read_b128 v[240:243], v173 offset:9280
	s_waitcnt lgkmcnt(4)
	v_mfma_f32_16x16x32_bf16 v[88:91], v[248:251], v[8:11], v[88:91]
	ds_read_b128 v[244:247], v173 offset:13824
	s_waitcnt lgkmcnt(4)
	v_mfma_f32_16x16x32_bf16 v[92:95], v[228:231], v[4:7], v[160:163]
	ds_read_b128 v[248:251], v173 offset:13888
	s_waitcnt lgkmcnt(4)
	v_mfma_f32_16x16x32_bf16 v[92:95], v[232:235], v[8:11], v[92:95]
	ds_read_b128 v[228:231], v173 offset:128
	s_waitcnt lgkmcnt(4)
	v_mfma_f32_16x16x32_bf16 v[96:99], v[236:239], v[4:7], v[176:179]
	ds_read_b128 v[232:235], v173 offset:192
	s_waitcnt lgkmcnt(4)
	v_mfma_f32_16x16x32_bf16 v[96:99], v[240:243], v[8:11], v[96:99]
	ds_read_b128 v[236:239], v173 offset:4736
	s_waitcnt lgkmcnt(4)
	v_mfma_f32_16x16x32_bf16 v[100:103], v[244:247], v[4:7], v[180:183]
	ds_read_b128 v[240:243], v173 offset:4800
	s_waitcnt lgkmcnt(4)
	v_mfma_f32_16x16x32_bf16 v[100:103], v[248:251], v[8:11], v[100:103]
	ds_read_b128 v[244:247], v173 offset:9344
	s_waitcnt lgkmcnt(4)
	v_mfma_f32_16x16x32_bf16 v[104:107], v[228:231], v[12:15], v[204:207]
	ds_read_b128 v[248:251], v173 offset:9408
	s_waitcnt lgkmcnt(4)
	v_mfma_f32_16x16x32_bf16 v[104:107], v[232:235], v[16:19], v[104:107]
	ds_read_b128 v[228:231], v173 offset:13952
	s_waitcnt lgkmcnt(4)
	v_mfma_f32_16x16x32_bf16 v[108:111], v[236:239], v[12:15], v[208:211]
	ds_read_b128 v[232:235], v173 offset:14016
	s_waitcnt lgkmcnt(4)
	v_mfma_f32_16x16x32_bf16 v[108:111], v[240:243], v[16:19], v[108:111]
	s_waitcnt lgkmcnt(3)
	v_mfma_f32_16x16x32_bf16 v[112:115], v[244:247], v[12:15], v[184:187]
	s_waitcnt lgkmcnt(2)
	v_mfma_f32_16x16x32_bf16 v[112:115], v[248:251], v[16:19], v[112:115]
	s_waitcnt lgkmcnt(1)
	v_mfma_f32_16x16x32_bf16 v[116:119], v[228:231], v[12:15], v[188:191]
	s_waitcnt lgkmcnt(0)
	v_mfma_f32_16x16x32_bf16 v[116:119], v[232:235], v[16:19], v[116:119]
	v_max3_f32 v26, v88, v89, v90
	v_max3_f32 v26, v26, v91, v92
	v_max3_f32 v26, v26, v93, v94
	v_max3_f32 v26, v26, v95, v96
	v_max3_f32 v26, v26, v97, v98
	v_max3_f32 v26, v26, v99, v100
	v_max3_f32 v26, v26, v101, v102
	v_max_f32_e32 v26, v26, v103
	v_cmp_lt_f32_e32 vcc, s66, v26
	s_cbranch_vccz .Ld_nr_A_0
	v_mov_b32_e32 v27, v26
	s_nop 1
	v_permlane16_swap_b32_e32 v26, v27
	v_max_f32_e32 v26, v26, v27
	v_mov_b32_e32 v27, v26
	s_nop 1
	v_permlane32_swap_b32_e32 v26, v27
	v_max_f32_e32 v26, v26, v27
	v_cmp_lt_f32_e32 vcc, s66, v26
	s_nop 1
	v_cndmask_b32_e32 v3, 0, v26, vcc
	v_sub_f32_e32 v2, 0, v3
	v_min_f32_e32 v2, 0, v2
	v_exp_f32_e32 v2, v2
	v_sub_f32_e32 v24, v24, v3
	v_mul_f32_e32 v0, v0, v2
	v_mul_f32_e32 v28, v28, v2
	v_mul_f32_e32 v29, v29, v2
	v_mul_f32_e32 v30, v30, v2
	v_mul_f32_e32 v31, v31, v2
	v_mul_f32_e32 v32, v32, v2
	v_mul_f32_e32 v33, v33, v2
	v_mul_f32_e32 v34, v34, v2
	v_mul_f32_e32 v35, v35, v2
	v_mul_f32_e32 v40, v40, v2
	v_mul_f32_e32 v41, v41, v2
	v_mul_f32_e32 v42, v42, v2
	v_mul_f32_e32 v43, v43, v2
	v_mul_f32_e32 v52, v52, v2
	v_mul_f32_e32 v53, v53, v2
	v_mul_f32_e32 v54, v54, v2
	v_mul_f32_e32 v55, v55, v2
	v_mul_f32_e32 v56, v56, v2
	v_mul_f32_e32 v57, v57, v2
	v_mul_f32_e32 v58, v58, v2
	v_mul_f32_e32 v59, v59, v2
	v_mul_f32_e32 v64, v64, v2
	v_mul_f32_e32 v65, v65, v2
	v_mul_f32_e32 v66, v66, v2
	v_mul_f32_e32 v67, v67, v2
	v_mul_f32_e32 v72, v72, v2
	v_mul_f32_e32 v73, v73, v2
	v_mul_f32_e32 v74, v74, v2
	v_mul_f32_e32 v75, v75, v2
	v_mul_f32_e32 v84, v84, v2
	v_mul_f32_e32 v85, v85, v2
	v_mul_f32_e32 v86, v86, v2
	v_mul_f32_e32 v87, v87, v2
	v_sub_f32_e32 v88, v88, v3
	v_sub_f32_e32 v89, v89, v3
	v_sub_f32_e32 v90, v90, v3
	v_sub_f32_e32 v91, v91, v3
	v_sub_f32_e32 v92, v92, v3
	v_sub_f32_e32 v93, v93, v3
	v_sub_f32_e32 v94, v94, v3
	v_sub_f32_e32 v95, v95, v3
	v_sub_f32_e32 v96, v96, v3
	v_sub_f32_e32 v97, v97, v3
	v_sub_f32_e32 v98, v98, v3
	v_sub_f32_e32 v99, v99, v3
	v_sub_f32_e32 v100, v100, v3
	v_sub_f32_e32 v101, v101, v3
	v_sub_f32_e32 v102, v102, v3
	v_sub_f32_e32 v103, v103, v3

.Ld_nr_A_1:
	v_exp_f32_e32 v104, v104
	v_exp_f32_e32 v105, v105
	v_exp_f32_e32 v106, v106
	v_exp_f32_e32 v107, v107
	v_exp_f32_e32 v108, v108
	v_exp_f32_e32 v109, v109
	v_exp_f32_e32 v110, v110
	v_exp_f32_e32 v111, v111
	v_exp_f32_e32 v112, v112
	v_exp_f32_e32 v113, v113
	v_exp_f32_e32 v114, v114
	v_exp_f32_e32 v115, v115
	v_exp_f32_e32 v116, v116
	v_exp_f32_e32 v117, v117
	v_exp_f32_e32 v118, v118
	v_exp_f32_e32 v119, v119
	s_nop 0
	v_add_f32_e32 v26, v104, v105
	v_add_f32_e32 v26, v26, v106
	v_add_f32_e32 v26, v26, v107
	v_add_f32_e32 v26, v26, v108
	v_add_f32_e32 v26, v26, v109
	v_add_f32_e32 v26, v26, v110
	v_add_f32_e32 v26, v26, v111
	v_add_f32_e32 v26, v26, v112
	v_add_f32_e32 v26, v26, v113
	v_add_f32_e32 v26, v26, v114
	v_add_f32_e32 v26, v26, v115
	v_add_f32_e32 v26, v26, v116
	v_add_f32_e32 v26, v26, v117
	v_add_f32_e32 v26, v26, v118
	v_add_f32_e32 v26, v26, v119
	v_add_f32_e32 v151, v151, v26
	v_cvt_pk_bf16_f32 v128, v104, v105
	v_cvt_pk_bf16_f32 v129, v106, v107
	v_cvt_pk_bf16_f32 v130, v108, v109
	v_cvt_pk_bf16_f32 v131, v110, v111
	v_cvt_pk_bf16_f32 v152, v112, v113
	v_cvt_pk_bf16_f32 v153, v114, v115
	v_cvt_pk_bf16_f32 v154, v116, v117
	v_cvt_pk_bf16_f32 v155, v118, v119
	v_add_f32_e32 v165, 0x42800000, v165
	v_mov_b32_e32 v156, v165
	v_add_f32_e32 v157, 0x3f800000, v165
	v_add_f32_e32 v158, 0x40000000, v165
	v_add_f32_e32 v159, 0x40400000, v165
	v_add_f32_e32 v160, 0x41800000, v165
	v_add_f32_e32 v161, 0x41880000, v165
	v_add_f32_e32 v162, 0x41900000, v165
	v_add_f32_e32 v163, 0x41980000, v165
	v_add_f32_e32 v176, 0x42000000, v165
	v_add_f32_e32 v177, 0x42040000, v165
	v_add_f32_e32 v178, 0x42080000, v165
	v_add_f32_e32 v179, 0x420c0000, v165
	v_add_f32_e32 v180, 0x42400000, v165
	v_add_f32_e32 v181, 0x42440000, v165
	v_add_f32_e32 v182, 0x42480000, v165
	v_add_f32_e32 v183, 0x424c0000, v165
	v_fma_f32 v204, -v150, |v156|, v25
	v_fma_f32 v205, -v150, |v157|, v25
	v_fma_f32 v206, -v150, |v158|, v25
	v_fma_f32 v207, -v150, |v159|, v25
	v_fma_f32 v208, -v150, |v160|, v25
	v_fma_f32 v209, -v150, |v161|, v25
	v_fma_f32 v210, -v150, |v162|, v25
	v_fma_f32 v211, -v150, |v163|, v25
	v_fma_f32 v184, -v150, |v176|, v25
	v_fma_f32 v185, -v150, |v177|, v25
	v_fma_f32 v186, -v150, |v178|, v25
	v_fma_f32 v187, -v150, |v179|, v25
	v_fma_f32 v188, -v150, |v180|, v25
	v_fma_f32 v189, -v150, |v181|, v25
	v_fma_f32 v190, -v150, |v182|, v25
	v_fma_f32 v191, -v150, |v183|, v25
	v_fma_f32 v156, -v150, |v156|, v24
	v_fma_f32 v157, -v150, |v157|, v24
	v_fma_f32 v158, -v150, |v158|, v24
	v_fma_f32 v159, -v150, |v159|, v24
	v_fma_f32 v160, -v150, |v160|, v24
	v_fma_f32 v161, -v150, |v161|, v24
	v_fma_f32 v162, -v150, |v162|, v24
	v_fma_f32 v163, -v150, |v163|, v24
	v_fma_f32 v176, -v150, |v176|, v24
	v_fma_f32 v177, -v150, |v177|, v24
	v_fma_f32 v178, -v150, |v178|, v24
	v_fma_f32 v179, -v150, |v179|, v24
	v_fma_f32 v180, -v150, |v180|, v24
	v_fma_f32 v181, -v150, |v181|, v24
	v_fma_f32 v182, -v150, |v182|, v24
	v_fma_f32 v183, -v150, |v183|, v24
	s_waitcnt vmcnt(0)
	ds_write_b128 v175, v[212:215]
	ds_write_b128 v175, v[216:219] offset:9216
	ds_write_b128 v164, v[220:223] offset:36864
	ds_write_b128 v164, v[224:227] offset:46080
	s_mov_b32 s31, s38
	s_mov_b32 s38, s39
	s_add_i32 s39, s39, 0x4800
	s_cmp_lg_u32 s39, 0xd800
	s_cselect_b32 s39, s39, 0
	s_mov_b32 s66, 0x42800000
	s_add_i32 s5, s5, 1
	s_min_u32 s8, s5, 62
	s_add_i32 s8, s8, 1
	s_mul_i32 s30, s8, 0xf8000
	s_waitcnt lgkmcnt(0)
	s_barrier
	s_cmp_lt_u32 s5, 64
	s_cbranch_scc1 .Ld_loopA
	v_add_u32_e32 v174, s31, v168
	ds_read_b64_tr_b16 v[228:229], v174 offset:36864
	ds_read_b64_tr_b16 v[230:231], v174 offset:41472
	ds_read_b64_tr_b16 v[232:233], v174 offset:36896
	ds_read_b64_tr_b16 v[234:235], v174 offset:41504
	ds_read_b64_tr_b16 v[236:237], v174 offset:36928
	ds_read_b64_tr_b16 v[238:239], v174 offset:41536
	ds_read_b64_tr_b16 v[240:241], v174 offset:36960
	ds_read_b64_tr_b16 v[242:243], v174 offset:41568
	ds_read_b64_tr_b16 v[244:245], v174 offset:36992
	ds_read_b64_tr_b16 v[246:247], v174 offset:41600
	s_waitcnt lgkmcnt(8)
	v_mfma_f32_16x16x32_bf16 v[28:31], v[228:231], v[120:123], v[28:31]
	v_mfma_f32_16x16x32_bf16 v[36:39], v[228:231], v[128:131], v[36:39]
	ds_read_b64_tr_b16 v[248:249], v174 offset:37024
	ds_read_b64_tr_b16 v[250:251], v174 offset:41632
	s_waitcnt lgkmcnt(8)
	v_mfma_f32_16x16x32_bf16 v[32:35], v[232:235], v[120:123], v[32:35]
	v_mfma_f32_16x16x32_bf16 v[44:47], v[232:235], v[128:131], v[44:47]
	ds_read_b64_tr_b16 v[228:229], v174 offset:37056
	ds_read_b64_tr_b16 v[230:231], v174 offset:41664
	s_waitcnt lgkmcnt(8)
	v_mfma_f32_16x16x32_bf16 v[40:43], v[236:239], v[120:123], v[40:43]
	v_mfma_f32_16x16x32_bf16 v[48:51], v[236:239], v[128:131], v[48:51]
	ds_read_b64_tr_b16 v[232:233], v174 offset:37088
	ds_read_b64_tr_b16 v[234:235], v174 offset:41696
	s_waitcnt lgkmcnt(8)
	v_mfma_f32_16x16x32_bf16 v[52:55], v[240:243], v[120:123], v[52:55]
	v_mfma_f32_16x16x32_bf16 v[60:63], v[240:243], v[128:131], v[60:63]
	ds_read_b64_tr_b16 v[236:237], v174 offset:46080
	ds_read_b64_tr_b16 v[238:239], v174 offset:50688
	s_waitcnt lgkmcnt(8)
	v_mfma_f32_16x16x32_bf16 v[56:59], v[244:247], v[120:123], v[56:59]
	v_mfma_f32_16x16x32_bf16 v[68:71], v[244:247], v[128:131], v[68:71]
	ds_read_b64_tr_b16 v[240:241], v174 offset:46112
	ds_read_b64_tr_b16 v[242:243], v174 offset:50720
	s_waitcnt lgkmcnt(8)
	v_mfma_f32_16x16x32_bf16 v[64:67], v[248:251], v[120:123], v[64:67]
	v_mfma_f32_16x16x32_bf16 v[76:79], v[248:251], v[128:131], v[76:79]
	ds_read_b64_tr_b16 v[244:245], v174 offset:46144
	ds_read_b64_tr_b16 v[246:247], v174 offset:50752
	s_waitcnt lgkmcnt(8)
	v_mfma_f32_16x16x32_bf16 v[72:75], v[228:231], v[120:123], v[72:75]
	v_mfma_f32_16x16x32_bf16 v[80:83], v[228:231], v[128:131], v[80:83]
	ds_read_b64_tr_b16 v[248:249], v174 offset:46176
	ds_read_b64_tr_b16 v[250:251], v174 offset:50784
	s_waitcnt lgkmcnt(8)
	v_mfma_f32_16x16x32_bf16 v[84:87], v[232:235], v[120:123], v[84:87]
	v_mfma_f32_16x16x32_bf16 v[20:23], v[232:235], v[128:131], v[20:23]
	ds_read_b64_tr_b16 v[228:229], v174 offset:46208
	ds_read_b64_tr_b16 v[230:231], v174 offset:50816
	s_waitcnt lgkmcnt(8)
	v_mfma_f32_16x16x32_bf16 v[28:31], v[236:239], v[124:127], v[28:31]
	v_mfma_f32_16x16x32_bf16 v[36:39], v[236:239], v[152:155], v[36:39]
	ds_read_b64_tr_b16 v[232:233], v174 offset:46240
	ds_read_b64_tr_b16 v[234:235], v174 offset:50848
	s_waitcnt lgkmcnt(8)
	v_mfma_f32_16x16x32_bf16 v[32:35], v[240:243], v[124:127], v[32:35]
	v_mfma_f32_16x16x32_bf16 v[44:47], v[240:243], v[152:155], v[44:47]
	ds_read_b64_tr_b16 v[236:237], v174 offset:46272
	ds_read_b64_tr_b16 v[238:239], v174 offset:50880
	s_waitcnt lgkmcnt(8)
	v_mfma_f32_16x16x32_bf16 v[40:43], v[244:247], v[124:127], v[40:43]
	v_mfma_f32_16x16x32_bf16 v[48:51], v[244:247], v[152:155], v[48:51]
	ds_read_b64_tr_b16 v[240:241], v174 offset:46304
	ds_read_b64_tr_b16 v[242:243], v174 offset:50912
	s_waitcnt lgkmcnt(8)
	v_mfma_f32_16x16x32_bf16 v[52:55], v[248:251], v[124:127], v[52:55]
	v_mfma_f32_16x16x32_bf16 v[60:63], v[248:251], v[152:155], v[60:63]
	s_waitcnt lgkmcnt(6)
	v_mfma_f32_16x16x32_bf16 v[56:59], v[228:231], v[124:127], v[56:59]
	v_mfma_f32_16x16x32_bf16 v[68:71], v[228:231], v[152:155], v[68:71]
	s_waitcnt lgkmcnt(4)
	v_mfma_f32_16x16x32_bf16 v[64:67], v[232:235], v[124:127], v[64:67]
	v_mfma_f32_16x16x32_bf16 v[76:79], v[232:235], v[152:155], v[76:79]
	s_waitcnt lgkmcnt(2)
	v_mfma_f32_16x16x32_bf16 v[72:75], v[236:239], v[124:127], v[72:75]
	v_mfma_f32_16x16x32_bf16 v[80:83], v[236:239], v[152:155], v[80:83]
	s_waitcnt lgkmcnt(0)
	v_mfma_f32_16x16x32_bf16 v[84:87], v[240:243], v[124:127], v[84:87]
	v_mfma_f32_16x16x32_bf16 v[20:23], v[240:243], v[152:155], v[20:23]

.Lb_nr_B_1:
	v_exp_f32_e32 v104, v104
	v_exp_f32_e32 v105, v105
	v_exp_f32_e32 v106, v106
	v_exp_f32_e32 v107, v107
	v_exp_f32_e32 v168, v168
	v_exp_f32_e32 v169, v169
	v_exp_f32_e32 v170, v170
	v_exp_f32_e32 v171, v171
	v_exp_f32_e32 v172, v172
	v_exp_f32_e32 v173, v173
	v_exp_f32_e32 v174, v174
	v_exp_f32_e32 v175, v175
	v_exp_f32_e32 v176, v176
	v_exp_f32_e32 v177, v177
	v_exp_f32_e32 v178, v178
	v_exp_f32_e32 v179, v179
	s_nop 0
	v_add_f32_e32 v67, v104, v105
	v_add_f32_e32 v67, v67, v106
	v_add_f32_e32 v67, v67, v107
	v_add_f32_e32 v67, v67, v168
	v_add_f32_e32 v67, v67, v169
	v_add_f32_e32 v67, v67, v170
	v_add_f32_e32 v67, v67, v171
	v_add_f32_e32 v67, v67, v172
	v_add_f32_e32 v67, v67, v173
	v_add_f32_e32 v67, v67, v174
	v_add_f32_e32 v67, v67, v175
	v_add_f32_e32 v67, v67, v176
	v_add_f32_e32 v67, v67, v177
	v_add_f32_e32 v67, v67, v178
	v_add_f32_e32 v67, v67, v179
	v_add_f32_e32 v64, v64, v67
	v_cvt_pk_bf16_f32 v184, v104, v105
	v_cvt_pk_bf16_f32 v185, v106, v107
	v_cvt_pk_bf16_f32 v186, v168, v169
	v_cvt_pk_bf16_f32 v187, v170, v171
	v_cvt_pk_bf16_f32 v204, v172, v173
	v_cvt_pk_bf16_f32 v205, v174, v175
	v_cvt_pk_bf16_f32 v206, v176, v177
	v_cvt_pk_bf16_f32 v207, v178, v179
	ds_read_b128 v[240:243], v71 offset:7680
	s_waitcnt lgkmcnt(6)
	v_mfma_f32_16x16x32_bf16 v[88:91], v[216:219], v[16:19], v[48:51]
	v_mfma_f32_16x16x32_bf16 v[104:107], v[216:219], v[12:15], v[52:55]
	ds_read_b128 v[244:247], v71 offset:7744
	s_waitcnt lgkmcnt(6)
	v_mfma_f32_16x16x32_bf16 v[88:91], v[220:223], v[8:11], v[88:91]
	v_mfma_f32_16x16x32_bf16 v[104:107], v[220:223], v[4:7], v[104:107]
	ds_read_b64_tr_b16 v[248:249], v72 offset:20480
	ds_read_b64_tr_b16 v[250:251], v72 offset:23040
	s_waitcnt lgkmcnt(7)
	v_mfma_f32_16x16x32_bf16 v[92:95], v[224:227], v[16:19], v[48:51]
	v_mfma_f32_16x16x32_bf16 v[168:171], v[224:227], v[12:15], v[52:55]
	ds_read_b64_tr_b16 v[216:217], v72 offset:20512
	ds_read_b64_tr_b16 v[218:219], v72 offset:23072
	s_waitcnt lgkmcnt(8)
	v_mfma_f32_16x16x32_bf16 v[92:95], v[228:231], v[8:11], v[92:95]
	v_mfma_f32_16x16x32_bf16 v[168:171], v[228:231], v[4:7], v[168:171]
	ds_read_b64_tr_b16 v[220:221], v72 offset:20544
	ds_read_b64_tr_b16 v[222:223], v72 offset:23104
	s_waitcnt lgkmcnt(9)
	v_mfma_f32_16x16x32_bf16 v[96:99], v[232:235], v[16:19], v[48:51]
	v_mfma_f32_16x16x32_bf16 v[172:175], v[232:235], v[12:15], v[52:55]
	ds_read_b64_tr_b16 v[224:225], v72 offset:20576
	ds_read_b64_tr_b16 v[226:227], v72 offset:23136
	s_waitcnt lgkmcnt(10)
	v_mfma_f32_16x16x32_bf16 v[96:99], v[236:239], v[8:11], v[96:99]
	v_mfma_f32_16x16x32_bf16 v[172:175], v[236:239], v[4:7], v[172:175]
	ds_read_b64_tr_b16 v[228:229], v72 offset:25600
	ds_read_b64_tr_b16 v[230:231], v72 offset:28160
	s_waitcnt lgkmcnt(11)
	v_mfma_f32_16x16x32_bf16 v[100:103], v[240:243], v[16:19], v[48:51]
	v_mfma_f32_16x16x32_bf16 v[176:179], v[240:243], v[12:15], v[52:55]
	ds_read_b64_tr_b16 v[232:233], v72 offset:25632
	ds_read_b64_tr_b16 v[234:235], v72 offset:28192
	s_waitcnt lgkmcnt(12)
	v_mfma_f32_16x16x32_bf16 v[100:103], v[244:247], v[8:11], v[100:103]
	v_mfma_f32_16x16x32_bf16 v[176:179], v[244:247], v[4:7], v[176:179]
	ds_read_b64_tr_b16 v[236:237], v72 offset:25664
	ds_read_b64_tr_b16 v[238:239], v72 offset:28224
	s_waitcnt lgkmcnt(12)
	v_mfma_f32_16x16x32_bf16 v[34:37], v[248:251], v[180:183], v[34:37]
	v_mfma_f32_16x16x32_bf16 v[20:23], v[248:251], v[184:187], v[20:23]
	ds_read_b64_tr_b16 v[240:241], v72 offset:25696
	ds_read_b64_tr_b16 v[242:243], v72 offset:28256
	s_waitcnt lgkmcnt(12)
	v_mfma_f32_16x16x32_bf16 v[42:45], v[216:219], v[180:183], v[42:45]
	v_mfma_f32_16x16x32_bf16 v[24:27], v[216:219], v[184:187], v[24:27]
	s_waitcnt lgkmcnt(10)
	v_mfma_f32_16x16x32_bf16 v[56:59], v[220:223], v[180:183], v[56:59]
	v_mfma_f32_16x16x32_bf16 v[38:41], v[220:223], v[184:187], v[38:41]
	s_waitcnt lgkmcnt(8)
	v_mfma_f32_16x16x32_bf16 v[60:63], v[224:227], v[180:183], v[60:63]
	v_mfma_f32_16x16x32_bf16 v[28:31], v[224:227], v[184:187], v[28:31]
	s_waitcnt lgkmcnt(6)
	v_mfma_f32_16x16x32_bf16 v[34:37], v[228:231], v[188:191], v[34:37]
	v_mfma_f32_16x16x32_bf16 v[20:23], v[228:231], v[204:207], v[20:23]
	s_waitcnt lgkmcnt(4)
	v_mfma_f32_16x16x32_bf16 v[42:45], v[232:235], v[188:191], v[42:45]
	v_mfma_f32_16x16x32_bf16 v[24:27], v[232:235], v[204:207], v[24:27]
	s_waitcnt lgkmcnt(2)
	v_mfma_f32_16x16x32_bf16 v[56:59], v[236:239], v[188:191], v[56:59]
	v_mfma_f32_16x16x32_bf16 v[38:41], v[236:239], v[204:207], v[38:41]
	s_waitcnt lgkmcnt(0)
	v_mfma_f32_16x16x32_bf16 v[60:63], v[240:243], v[188:191], v[60:63]
	v_mfma_f32_16x16x32_bf16 v[28:31], v[240:243], v[204:207], v[28:31]
	s_waitcnt vmcnt(0)
	ds_write_b128 v73, v[208:211]
	ds_write_b128 v74, v[212:215] offset:20480
	s_mov_b32 s42, s43
	s_mov_b32 s43, s51
	s_add_i32 s51, s51, 10240
	s_cmp_lg_u32 s51, 30720
	s_cselect_b32 s51, s51, 0
	s_mov_b32 s66, 0xff800000
	s_cmp_ge_u32 s20, 1
	s_cselect_b32 s66, 0x42800000, s66
	s_add_i32 s20, s20, 1
	s_min_u32 s8, s20, 62
	s_add_i32 s8, s8, 1
	s_mul_i32 s30, s8, 0xf8000
	s_waitcnt lgkmcnt(0)
	s_barrier
	s_cmp_lt_u32 s20, 64
	s_cbranch_scc1 .Lb_loopB
	v_add_u32_e32 v72, s42, v119
	ds_read_b64_tr_b16 v[216:217], v72 offset:20480
	ds_read_b64_tr_b16 v[218:219], v72 offset:23040
	ds_read_b64_tr_b16 v[220:221], v72 offset:20512
	ds_read_b64_tr_b16 v[222:223], v72 offset:23072
	ds_read_b64_tr_b16 v[224:225], v72 offset:20544
	ds_read_b64_tr_b16 v[226:227], v72 offset:23104
	ds_read_b64_tr_b16 v[228:229], v72 offset:20576
	ds_read_b64_tr_b16 v[230:231], v72 offset:23136
	ds_read_b64_tr_b16 v[232:233], v72 offset:25600
	ds_read_b64_tr_b16 v[234:235], v72 offset:28160
	ds_read_b64_tr_b16 v[236:237], v72 offset:25632
	ds_read_b64_tr_b16 v[238:239], v72 offset:28192
	v_max3_f32 v67, v88, v89, v90
	v_max3_f32 v67, v67, v91, v92
	v_max3_f32 v67, v67, v93, v94
	v_max3_f32 v67, v67, v95, v96
	v_max3_f32 v67, v67, v97, v98
	v_max3_f32 v67, v67, v99, v100
	v_max3_f32 v67, v67, v101, v102
	v_max_f32_e32 v67, v67, v103
	v_cmp_lt_f32_e32 vcc, s66, v67
	s_cbranch_vccz .Lb_nr_Bt_0
	v_mov_b32_e32 v68, v67
	s_nop 1
	v_permlane16_swap_b32_e32 v67, v68
	v_max_f32_e32 v67, v67, v68
	v_mov_b32_e32 v68, v67
	s_nop 1
	v_permlane32_swap_b32_e32 v67, v68
	v_max_f32_e32 v67, v67, v68
	v_cmp_lt_f32_e32 vcc, s66, v67
	s_nop 1
	v_cndmask_b32_e32 v69, 0, v67, vcc
	v_sub_f32_e32 v70, 0, v69
	v_min_f32_e32 v70, 0, v70
	v_exp_f32_e32 v70, v70
	v_sub_f32_e32 v48, v48, v69
	v_sub_f32_e32 v49, v49, v69
	v_sub_f32_e32 v50, v50, v69
	v_sub_f32_e32 v51, v51, v69
	v_mul_f32_e32 v80, v80, v70
	v_mul_f32_e32 v34, v34, v70
	v_mul_f32_e32 v35, v35, v70
	v_mul_f32_e32 v36, v36, v70
	v_mul_f32_e32 v37, v37, v70
	v_mul_f32_e32 v42, v42, v70
	v_mul_f32_e32 v43, v43, v70
	v_mul_f32_e32 v44, v44, v70
	v_mul_f32_e32 v45, v45, v70
	v_mul_f32_e32 v56, v56, v70
	v_mul_f32_e32 v57, v57, v70
	v_mul_f32_e32 v58, v58, v70
	v_mul_f32_e32 v59, v59, v70
	v_mul_f32_e32 v60, v60, v70
	v_mul_f32_e32 v61, v61, v70
	v_mul_f32_e32 v62, v62, v70
	v_mul_f32_e32 v63, v63, v70
	v_sub_f32_e32 v88, v88, v69
	v_sub_f32_e32 v89, v89, v69
	v_sub_f32_e32 v90, v90, v69
	v_sub_f32_e32 v91, v91, v69
	v_sub_f32_e32 v92, v92, v69
	v_sub_f32_e32 v93, v93, v69
	v_sub_f32_e32 v94, v94, v69
	v_sub_f32_e32 v95, v95, v69
	v_sub_f32_e32 v96, v96, v69
	v_sub_f32_e32 v97, v97, v69
	v_sub_f32_e32 v98, v98, v69
	v_sub_f32_e32 v99, v99, v69
	v_sub_f32_e32 v100, v100, v69
	v_sub_f32_e32 v101, v101, v69
	v_sub_f32_e32 v102, v102, v69
	v_sub_f32_e32 v103, v103, v69

.Lb_nr_A_1:
	v_exp_f32_e32 v104, v104
	v_exp_f32_e32 v105, v105
	v_exp_f32_e32 v106, v106
	v_exp_f32_e32 v107, v107
	v_exp_f32_e32 v168, v168
	v_exp_f32_e32 v169, v169
	v_exp_f32_e32 v170, v170
	v_exp_f32_e32 v171, v171
	v_exp_f32_e32 v172, v172
	v_exp_f32_e32 v173, v173
	v_exp_f32_e32 v174, v174
	v_exp_f32_e32 v175, v175
	v_exp_f32_e32 v176, v176
	v_exp_f32_e32 v177, v177
	v_exp_f32_e32 v178, v178
	v_exp_f32_e32 v179, v179
	s_nop 0
	v_add_f32_e32 v67, v104, v105
	v_add_f32_e32 v67, v67, v106
	v_add_f32_e32 v67, v67, v107
	v_add_f32_e32 v67, v67, v168
	v_add_f32_e32 v67, v67, v169
	v_add_f32_e32 v67, v67, v170
	v_add_f32_e32 v67, v67, v171
	v_add_f32_e32 v67, v67, v172
	v_add_f32_e32 v67, v67, v173
	v_add_f32_e32 v67, v67, v174
	v_add_f32_e32 v67, v67, v175
	v_add_f32_e32 v67, v67, v176
	v_add_f32_e32 v67, v67, v177
	v_add_f32_e32 v67, v67, v178
	v_add_f32_e32 v67, v67, v179
	v_add_f32_e32 v64, v64, v67
	v_cvt_pk_bf16_f32 v184, v104, v105
	v_cvt_pk_bf16_f32 v185, v106, v107
	v_cvt_pk_bf16_f32 v186, v168, v169
	v_cvt_pk_bf16_f32 v187, v170, v171
	v_cvt_pk_bf16_f32 v204, v172, v173
	v_cvt_pk_bf16_f32 v205, v174, v175
	v_cvt_pk_bf16_f32 v206, v176, v177
	v_cvt_pk_bf16_f32 v207, v178, v179
	s_waitcnt vmcnt(0)
	ds_write_b128 v73, v[208:211]
	ds_write_b128 v74, v[212:215] offset:20480
	s_mov_b32 s66, 0x42800000
	s_add_i32 s20, s20, 1
	s_waitcnt lgkmcnt(0)
	s_barrier
	s_cmp_lt_u32 s20, 64
	s_cbranch_scc1 .Lb_loopA
	v_add_u32_e32 v72, s42, v119
	ds_read_b64_tr_b16 v[216:217], v72 offset:20480
	ds_read_b64_tr_b16 v[218:219], v72 offset:23040
	ds_read_b64_tr_b16 v[220:221], v72 offset:20512
	ds_read_b64_tr_b16 v[222:223], v72 offset:23072
	ds_read_b64_tr_b16 v[224:225], v72 offset:20544
	ds_read_b64_tr_b16 v[226:227], v72 offset:23104
	ds_read_b64_tr_b16 v[228:229], v72 offset:20576
	ds_read_b64_tr_b16 v[230:231], v72 offset:23136
	ds_read_b64_tr_b16 v[232:233], v72 offset:25600
	ds_read_b64_tr_b16 v[234:235], v72 offset:28160
	ds_read_b64_tr_b16 v[236:237], v72 offset:25632
	ds_read_b64_tr_b16 v[238:239], v72 offset:28192
	ds_read_b64_tr_b16 v[240:241], v72 offset:25664
	ds_read_b64_tr_b16 v[242:243], v72 offset:28224
	s_waitcnt lgkmcnt(12)
	v_mfma_f32_16x16x32_bf16 v[34:37], v[216:219], v[180:183], v[34:37]
	v_mfma_f32_16x16x32_bf16 v[20:23], v[216:219], v[184:187], v[20:23]
	ds_read_b64_tr_b16 v[244:245], v72 offset:25696
	ds_read_b64_tr_b16 v[246:247], v72 offset:28256
	s_waitcnt lgkmcnt(12)
	v_mfma_f32_16x16x32_bf16 v[42:45], v[220:223], v[180:183], v[42:45]
	v_mfma_f32_16x16x32_bf16 v[24:27], v[220:223], v[184:187], v[24:27]
	s_waitcnt lgkmcnt(10)
	v_mfma_f32_16x16x32_bf16 v[56:59], v[224:227], v[180:183], v[56:59]
	v_mfma_f32_16x16x32_bf16 v[38:41], v[224:227], v[184:187], v[38:41]
	s_waitcnt lgkmcnt(8)
	v_mfma_f32_16x16x32_bf16 v[60:63], v[228:231], v[180:183], v[60:63]
	v_mfma_f32_16x16x32_bf16 v[28:31], v[228:231], v[184:187], v[28:31]
	s_waitcnt lgkmcnt(6)
	v_mfma_f32_16x16x32_bf16 v[34:37], v[232:235], v[188:191], v[34:37]
	v_mfma_f32_16x16x32_bf16 v[20:23], v[232:235], v[204:207], v[20:23]
	s_waitcnt lgkmcnt(4)
	v_mfma_f32_16x16x32_bf16 v[42:45], v[236:239], v[188:191], v[42:45]
	v_mfma_f32_16x16x32_bf16 v[24:27], v[236:239], v[204:207], v[24:27]
	s_waitcnt lgkmcnt(2)
	v_mfma_f32_16x16x32_bf16 v[56:59], v[240:243], v[188:191], v[56:59]
	v_mfma_f32_16x16x32_bf16 v[38:41], v[240:243], v[204:207], v[38:41]
	s_waitcnt lgkmcnt(0)
	v_mfma_f32_16x16x32_bf16 v[60:63], v[244:247], v[188:191], v[60:63]
	v_mfma_f32_16x16x32_bf16 v[28:31], v[244:247], v[204:207], v[28:31]

.LBB0_1010:
	s_add_u32 s80, s18, 0x9504000
	s_addc_u32 s81, s19, 0
	s_add_u32 s86, s80, 0x1f0000
	s_addc_u32 s87, s81, 0
	s_add_u32 s96, s6, 0x1404000
	s_addc_u32 s97, s7, 0
	s_add_u32 s98, s96, 0x10000
	s_addc_u32 s99, s97, 0
	v_subrev_u32_e32 v190, s18, v190
	v_add_u32_e32 v191, 0xf8000, v190
	v_subrev_u32_e32 v188, s6, v188
	v_add_u32_e32 v207, 0xa000, v206
	global_load_dwordx4 v[228:231], v190, s[80:81] offset:128
	global_load_dwordx4 v[232:235], v191, s[80:81] offset:128
	global_load_dwordx4 v[236:239], v190, s[86:87] offset:128
	global_load_dwordx4 v[240:243], v191, s[86:87] offset:128
	global_load_dwordx4 v[244:247], v188, s[96:97] offset:128
	global_load_dwordx4 v[248:251], v188, s[98:99] offset:128
	global_load_dwordx4 v[66:69], v190, s[80:81] offset:256
	global_load_dwordx4 v[70:73], v191, s[80:81] offset:256
	global_load_dwordx4 v[74:77], v190, s[86:87] offset:256
	global_load_dwordx4 v[78:81], v191, s[86:87] offset:256
	global_load_dwordx4 v[82:85], v188, s[96:97] offset:256
	global_load_dwordx4 v[86:89], v188, s[98:99] offset:256
	ds_read_b128 v[90:93], v119 offset:0
	ds_read_b128 v[208:211], v205 offset:0
	ds_read_b128 v[212:215], v119 offset:2560
	ds_read_b128 v[216:219], v119 offset:5120
	ds_read_b128 v[220:223], v119 offset:7680
	s_waitcnt lgkmcnt(3)
	v_mfma_f32_16x16x32_bf16 v[6:9], v[90:93], v[208:211], v[6:9]
	s_waitcnt lgkmcnt(2)
	v_mfma_f32_16x16x32_bf16 v[30:33], v[212:215], v[208:211], v[30:33]
	s_waitcnt vmcnt(11)
	ds_write_b128 v207, v[228:231] offset:0
	s_waitcnt lgkmcnt(2)
	v_mfma_f32_16x16x32_bf16 v[38:41], v[216:219], v[208:211], v[38:41]
	s_waitcnt lgkmcnt(1)
	v_mfma_f32_16x16x32_bf16 v[42:45], v[220:223], v[208:211], v[42:45]
	ds_read_b128 v[208:211], v205 offset:2560
	s_waitcnt lgkmcnt(0)
	v_mfma_f32_16x16x32_bf16 v[46:49], v[90:93], v[208:211], v[46:49]
	v_mfma_f32_16x16x32_bf16 v[26:29], v[212:215], v[208:211], v[26:29]
	s_waitcnt vmcnt(10)
	ds_write_b128 v207, v[232:235] offset:10240
	v_mfma_f32_16x16x32_bf16 v[14:17], v[216:219], v[208:211], v[14:17]
	v_mfma_f32_16x16x32_bf16 v[10:13], v[220:223], v[208:211], v[10:13]
	ds_read_b128 v[208:211], v205 offset:5120
	s_waitcnt lgkmcnt(0)
	v_mfma_f32_16x16x32_bf16 v[34:37], v[90:93], v[208:211], v[34:37]
	v_mfma_f32_16x16x32_bf16 v[22:25], v[212:215], v[208:211], v[22:25]
	s_waitcnt vmcnt(9)
	ds_write_b128 v207, v[236:239] offset:20480
	v_mfma_f32_16x16x32_bf16 v[18:21], v[216:219], v[208:211], v[18:21]
	v_mfma_f32_16x16x32_bf16 v[62:65], v[220:223], v[208:211], v[62:65]
	ds_read_b128 v[208:211], v205 offset:7680
	s_waitcnt lgkmcnt(0)
	v_mfma_f32_16x16x32_bf16 v[58:61], v[90:93], v[208:211], v[58:61]
	ds_read_b128 v[90:93], v119 offset:64
	v_mfma_f32_16x16x32_bf16 v[54:57], v[212:215], v[208:211], v[54:57]
	s_waitcnt vmcnt(8)
	ds_write_b128 v207, v[240:243] offset:30720
	ds_read_b128 v[212:215], v119 offset:2624
	v_mfma_f32_16x16x32_bf16 v[50:53], v[216:219], v[208:211], v[50:53]
	ds_read_b128 v[216:219], v119 offset:5184
	v_mfma_f32_16x16x32_bf16 v[2:5], v[220:223], v[208:211], v[2:5]
	ds_read_b128 v[220:223], v119 offset:7744
	ds_read_b128 v[208:211], v205 offset:64
	ds_read_b128 v[224:227], v205 offset:7744
	s_waitcnt lgkmcnt(1)
	v_mfma_f32_16x16x32_bf16 v[6:9], v[90:93], v[208:211], v[6:9]
	v_mfma_f32_16x16x32_bf16 v[30:33], v[212:215], v[208:211], v[30:33]
	s_waitcnt vmcnt(7)
	ds_write_b128 v0, v[244:247] offset:20480
	v_mfma_f32_16x16x32_bf16 v[38:41], v[216:219], v[208:211], v[38:41]
	v_mfma_f32_16x16x32_bf16 v[42:45], v[220:223], v[208:211], v[42:45]
	ds_read_b128 v[208:211], v205 offset:2624
	s_waitcnt lgkmcnt(0)
	v_mfma_f32_16x16x32_bf16 v[46:49], v[90:93], v[208:211], v[46:49]
	v_mfma_f32_16x16x32_bf16 v[26:29], v[212:215], v[208:211], v[26:29]
	s_waitcnt vmcnt(6)
	ds_write_b128 v0, v[248:251] offset:30720
	v_mfma_f32_16x16x32_bf16 v[14:17], v[216:219], v[208:211], v[14:17]
	v_mfma_f32_16x16x32_bf16 v[10:13], v[220:223], v[208:211], v[10:13]
	ds_read_b128 v[208:211], v205 offset:5184
	s_waitcnt lgkmcnt(0)
	v_mfma_f32_16x16x32_bf16 v[34:37], v[90:93], v[208:211], v[34:37]
	v_mfma_f32_16x16x32_bf16 v[22:25], v[212:215], v[208:211], v[22:25]
	v_mfma_f32_16x16x32_bf16 v[18:21], v[216:219], v[208:211], v[18:21]
	v_mfma_f32_16x16x32_bf16 v[62:65], v[220:223], v[208:211], v[62:65]
	v_mfma_f32_16x16x32_bf16 v[58:61], v[90:93], v[224:227], v[58:61]
	s_waitcnt lgkmcnt(0)
	v_mfma_f32_16x16x32_bf16 v[54:57], v[212:215], v[224:227], v[54:57]
	s_barrier
	v_mfma_f32_16x16x32_bf16 v[50:53], v[216:219], v[224:227], v[50:53]
	v_mfma_f32_16x16x32_bf16 v[2:5], v[220:223], v[224:227], v[2:5]
	global_load_dwordx4 v[228:231], v190, s[80:81] offset:384
	global_load_dwordx4 v[232:235], v191, s[80:81] offset:384
	global_load_dwordx4 v[236:239], v190, s[86:87] offset:384
	global_load_dwordx4 v[240:243], v191, s[86:87] offset:384
	global_load_dwordx4 v[244:247], v188, s[96:97] offset:384
	global_load_dwordx4 v[248:251], v188, s[98:99] offset:384
	ds_read_b128 v[90:93], v119 offset:20480
	ds_read_b128 v[208:211], v205 offset:40960
	ds_read_b128 v[212:215], v119 offset:23040
	ds_read_b128 v[216:219], v119 offset:25600
	ds_read_b128 v[220:223], v119 offset:28160
	s_waitcnt lgkmcnt(3)
	v_mfma_f32_16x16x32_bf16 v[6:9], v[90:93], v[208:211], v[6:9]
	s_waitcnt lgkmcnt(2)
	v_mfma_f32_16x16x32_bf16 v[30:33], v[212:215], v[208:211], v[30:33]
	s_waitcnt vmcnt(11)
	ds_write_b128 v206, v[66:69] offset:0
	s_waitcnt lgkmcnt(2)
	v_mfma_f32_16x16x32_bf16 v[38:41], v[216:219], v[208:211], v[38:41]
	s_waitcnt lgkmcnt(1)
	v_mfma_f32_16x16x32_bf16 v[42:45], v[220:223], v[208:211], v[42:45]
	ds_read_b128 v[208:211], v205 offset:43520
	s_waitcnt lgkmcnt(0)
	v_mfma_f32_16x16x32_bf16 v[46:49], v[90:93], v[208:211], v[46:49]
	v_mfma_f32_16x16x32_bf16 v[26:29], v[212:215], v[208:211], v[26:29]
	s_waitcnt vmcnt(10)
	ds_write_b128 v206, v[70:73] offset:10240
	v_mfma_f32_16x16x32_bf16 v[14:17], v[216:219], v[208:211], v[14:17]
	v_mfma_f32_16x16x32_bf16 v[10:13], v[220:223], v[208:211], v[10:13]
	ds_read_b128 v[208:211], v205 offset:46080
	s_waitcnt lgkmcnt(0)
	v_mfma_f32_16x16x32_bf16 v[34:37], v[90:93], v[208:211], v[34:37]
	v_mfma_f32_16x16x32_bf16 v[22:25], v[212:215], v[208:211], v[22:25]
	s_waitcnt vmcnt(9)
	ds_write_b128 v206, v[74:77] offset:20480
	v_mfma_f32_16x16x32_bf16 v[18:21], v[216:219], v[208:211], v[18:21]
	v_mfma_f32_16x16x32_bf16 v[62:65], v[220:223], v[208:211], v[62:65]
	ds_read_b128 v[208:211], v205 offset:48640
	s_waitcnt lgkmcnt(0)
	v_mfma_f32_16x16x32_bf16 v[58:61], v[90:93], v[208:211], v[58:61]
	ds_read_b128 v[90:93], v119 offset:20544
	v_mfma_f32_16x16x32_bf16 v[54:57], v[212:215], v[208:211], v[54:57]
	s_waitcnt vmcnt(8)
	ds_write_b128 v206, v[78:81] offset:30720
	ds_read_b128 v[212:215], v119 offset:23104
	v_mfma_f32_16x16x32_bf16 v[50:53], v[216:219], v[208:211], v[50:53]
	ds_read_b128 v[216:219], v119 offset:25664
	v_mfma_f32_16x16x32_bf16 v[2:5], v[220:223], v[208:211], v[2:5]
	ds_read_b128 v[220:223], v119 offset:28224
	ds_read_b128 v[208:211], v205 offset:41024
	ds_read_b128 v[224:227], v205 offset:48704
	s_waitcnt lgkmcnt(1)
	v_mfma_f32_16x16x32_bf16 v[6:9], v[90:93], v[208:211], v[6:9]
	v_mfma_f32_16x16x32_bf16 v[30:33], v[212:215], v[208:211], v[30:33]
	s_waitcnt vmcnt(7)
	ds_write_b128 v0, v[82:85] offset:0
	v_mfma_f32_16x16x32_bf16 v[38:41], v[216:219], v[208:211], v[38:41]
	v_mfma_f32_16x16x32_bf16 v[42:45], v[220:223], v[208:211], v[42:45]
	ds_read_b128 v[208:211], v205 offset:43584
	s_waitcnt lgkmcnt(0)
	v_mfma_f32_16x16x32_bf16 v[46:49], v[90:93], v[208:211], v[46:49]
	v_mfma_f32_16x16x32_bf16 v[26:29], v[212:215], v[208:211], v[26:29]
	s_waitcnt vmcnt(6)
	ds_write_b128 v0, v[86:89] offset:10240
	v_mfma_f32_16x16x32_bf16 v[14:17], v[216:219], v[208:211], v[14:17]
	v_mfma_f32_16x16x32_bf16 v[10:13], v[220:223], v[208:211], v[10:13]
	ds_read_b128 v[208:211], v205 offset:46144
	s_waitcnt lgkmcnt(0)
	v_mfma_f32_16x16x32_bf16 v[34:37], v[90:93], v[208:211], v[34:37]
	v_mfma_f32_16x16x32_bf16 v[22:25], v[212:215], v[208:211], v[22:25]
	v_mfma_f32_16x16x32_bf16 v[18:21], v[216:219], v[208:211], v[18:21]
	v_mfma_f32_16x16x32_bf16 v[62:65], v[220:223], v[208:211], v[62:65]
	v_mfma_f32_16x16x32_bf16 v[58:61], v[90:93], v[224:227], v[58:61]
	s_waitcnt lgkmcnt(0)
	v_mfma_f32_16x16x32_bf16 v[54:57], v[212:215], v[224:227], v[54:57]
	s_barrier
	v_mfma_f32_16x16x32_bf16 v[50:53], v[216:219], v[224:227], v[50:53]
	v_mfma_f32_16x16x32_bf16 v[2:5], v[220:223], v[224:227], v[2:5]
	global_load_dwordx4 v[66:69], v190, s[80:81] offset:512
	global_load_dwordx4 v[70:73], v191, s[80:81] offset:512
	global_load_dwordx4 v[74:77], v190, s[86:87] offset:512
	global_load_dwordx4 v[78:81], v191, s[86:87] offset:512
	global_load_dwordx4 v[82:85], v188, s[96:97] offset:512
	global_load_dwordx4 v[86:89], v188, s[98:99] offset:512
	ds_read_b128 v[90:93], v119 offset:0
	ds_read_b128 v[208:211], v205 offset:0
	ds_read_b128 v[212:215], v119 offset:2560
	ds_read_b128 v[216:219], v119 offset:5120
	ds_read_b128 v[220:223], v119 offset:7680
	s_waitcnt lgkmcnt(3)
	v_mfma_f32_16x16x32_bf16 v[6:9], v[90:93], v[208:211], v[6:9]
	s_waitcnt lgkmcnt(2)
	v_mfma_f32_16x16x32_bf16 v[30:33], v[212:215], v[208:211], v[30:33]
	s_waitcnt vmcnt(11)
	ds_write_b128 v207, v[228:231] offset:0
	s_waitcnt lgkmcnt(2)
	v_mfma_f32_16x16x32_bf16 v[38:41], v[216:219], v[208:211], v[38:41]
	s_waitcnt lgkmcnt(1)
	v_mfma_f32_16x16x32_bf16 v[42:45], v[220:223], v[208:211], v[42:45]
	ds_read_b128 v[208:211], v205 offset:2560
	s_waitcnt lgkmcnt(0)
	v_mfma_f32_16x16x32_bf16 v[46:49], v[90:93], v[208:211], v[46:49]
	v_mfma_f32_16x16x32_bf16 v[26:29], v[212:215], v[208:211], v[26:29]
	s_waitcnt vmcnt(10)
	ds_write_b128 v207, v[232:235] offset:10240
	v_mfma_f32_16x16x32_bf16 v[14:17], v[216:219], v[208:211], v[14:17]
	v_mfma_f32_16x16x32_bf16 v[10:13], v[220:223], v[208:211], v[10:13]
	ds_read_b128 v[208:211], v205 offset:5120
	s_waitcnt lgkmcnt(0)
	v_mfma_f32_16x16x32_bf16 v[34:37], v[90:93], v[208:211], v[34:37]
	v_mfma_f32_16x16x32_bf16 v[22:25], v[212:215], v[208:211], v[22:25]
	s_waitcnt vmcnt(9)
	ds_write_b128 v207, v[236:239] offset:20480
	v_mfma_f32_16x16x32_bf16 v[18:21], v[216:219], v[208:211], v[18:21]
	v_mfma_f32_16x16x32_bf16 v[62:65], v[220:223], v[208:211], v[62:65]
	ds_read_b128 v[208:211], v205 offset:7680
	s_waitcnt lgkmcnt(0)
	v_mfma_f32_16x16x32_bf16 v[58:61], v[90:93], v[208:211], v[58:61]
	ds_read_b128 v[90:93], v119 offset:64
	v_mfma_f32_16x16x32_bf16 v[54:57], v[212:215], v[208:211], v[54:57]
	s_waitcnt vmcnt(8)
	ds_write_b128 v207, v[240:243] offset:30720
	ds_read_b128 v[212:215], v119 offset:2624
	v_mfma_f32_16x16x32_bf16 v[50:53], v[216:219], v[208:211], v[50:53]
	ds_read_b128 v[216:219], v119 offset:5184
	v_mfma_f32_16x16x32_bf16 v[2:5], v[220:223], v[208:211], v[2:5]
	ds_read_b128 v[220:223], v119 offset:7744
	ds_read_b128 v[208:211], v205 offset:64
	ds_read_b128 v[224:227], v205 offset:7744
	s_waitcnt lgkmcnt(1)
	v_mfma_f32_16x16x32_bf16 v[6:9], v[90:93], v[208:211], v[6:9]
	v_mfma_f32_16x16x32_bf16 v[30:33], v[212:215], v[208:211], v[30:33]
	s_waitcnt vmcnt(7)
	ds_write_b128 v0, v[244:247] offset:20480
	v_mfma_f32_16x16x32_bf16 v[38:41], v[216:219], v[208:211], v[38:41]
	v_mfma_f32_16x16x32_bf16 v[42:45], v[220:223], v[208:211], v[42:45]
	ds_read_b128 v[208:211], v205 offset:2624
	s_waitcnt lgkmcnt(0)
	v_mfma_f32_16x16x32_bf16 v[46:49], v[90:93], v[208:211], v[46:49]
	v_mfma_f32_16x16x32_bf16 v[26:29], v[212:215], v[208:211], v[26:29]
	s_waitcnt vmcnt(6)
	ds_write_b128 v0, v[248:251] offset:30720
	v_mfma_f32_16x16x32_bf16 v[14:17], v[216:219], v[208:211], v[14:17]
	v_mfma_f32_16x16x32_bf16 v[10:13], v[220:223], v[208:211], v[10:13]
	ds_read_b128 v[208:211], v205 offset:5184
	s_waitcnt lgkmcnt(0)
	v_mfma_f32_16x16x32_bf16 v[34:37], v[90:93], v[208:211], v[34:37]
	v_mfma_f32_16x16x32_bf16 v[22:25], v[212:215], v[208:211], v[22:25]
	v_mfma_f32_16x16x32_bf16 v[18:21], v[216:219], v[208:211], v[18:21]
	v_mfma_f32_16x16x32_bf16 v[62:65], v[220:223], v[208:211], v[62:65]
	v_mfma_f32_16x16x32_bf16 v[58:61], v[90:93], v[224:227], v[58:61]
	s_waitcnt lgkmcnt(0)
	v_mfma_f32_16x16x32_bf16 v[54:57], v[212:215], v[224:227], v[54:57]
	s_barrier
	v_mfma_f32_16x16x32_bf16 v[50:53], v[216:219], v[224:227], v[50:53]
	v_mfma_f32_16x16x32_bf16 v[2:5], v[220:223], v[224:227], v[2:5]
	global_load_dwordx4 v[228:231], v190, s[80:81] offset:640
	global_load_dwordx4 v[232:235], v191, s[80:81] offset:640
	global_load_dwordx4 v[236:239], v190, s[86:87] offset:640
	global_load_dwordx4 v[240:243], v191, s[86:87] offset:640
	global_load_dwordx4 v[244:247], v188, s[96:97] offset:640
	global_load_dwordx4 v[248:251], v188, s[98:99] offset:640
	ds_read_b128 v[90:93], v119 offset:20480
	ds_read_b128 v[208:211], v205 offset:40960
	ds_read_b128 v[212:215], v119 offset:23040
	ds_read_b128 v[216:219], v119 offset:25600
	ds_read_b128 v[220:223], v119 offset:28160
	s_waitcnt lgkmcnt(3)
	v_mfma_f32_16x16x32_bf16 v[6:9], v[90:93], v[208:211], v[6:9]
	s_waitcnt lgkmcnt(2)
	v_mfma_f32_16x16x32_bf16 v[30:33], v[212:215], v[208:211], v[30:33]
	s_waitcnt vmcnt(11)
	ds_write_b128 v206, v[66:69] offset:0
	s_waitcnt lgkmcnt(2)
	v_mfma_f32_16x16x32_bf16 v[38:41], v[216:219], v[208:211], v[38:41]
	s_waitcnt lgkmcnt(1)
	v_mfma_f32_16x16x32_bf16 v[42:45], v[220:223], v[208:211], v[42:45]
	ds_read_b128 v[208:211], v205 offset:43520
	s_waitcnt lgkmcnt(0)
	v_mfma_f32_16x16x32_bf16 v[46:49], v[90:93], v[208:211], v[46:49]
	v_mfma_f32_16x16x32_bf16 v[26:29], v[212:215], v[208:211], v[26:29]
	s_waitcnt vmcnt(10)
	ds_write_b128 v206, v[70:73] offset:10240
	v_mfma_f32_16x16x32_bf16 v[14:17], v[216:219], v[208:211], v[14:17]
	v_mfma_f32_16x16x32_bf16 v[10:13], v[220:223], v[208:211], v[10:13]
	ds_read_b128 v[208:211], v205 offset:46080
	s_waitcnt lgkmcnt(0)
	v_mfma_f32_16x16x32_bf16 v[34:37], v[90:93], v[208:211], v[34:37]
	v_mfma_f32_16x16x32_bf16 v[22:25], v[212:215], v[208:211], v[22:25]
	s_waitcnt vmcnt(9)
	ds_write_b128 v206, v[74:77] offset:20480
	v_mfma_f32_16x16x32_bf16 v[18:21], v[216:219], v[208:211], v[18:21]
	v_mfma_f32_16x16x32_bf16 v[62:65], v[220:223], v[208:211], v[62:65]
	ds_read_b128 v[208:211], v205 offset:48640
	s_waitcnt lgkmcnt(0)
	v_mfma_f32_16x16x32_bf16 v[58:61], v[90:93], v[208:211], v[58:61]
	ds_read_b128 v[90:93], v119 offset:20544
	v_mfma_f32_16x16x32_bf16 v[54:57], v[212:215], v[208:211], v[54:57]
	s_waitcnt vmcnt(8)
	ds_write_b128 v206, v[78:81] offset:30720
	ds_read_b128 v[212:215], v119 offset:23104
	v_mfma_f32_16x16x32_bf16 v[50:53], v[216:219], v[208:211], v[50:53]
	ds_read_b128 v[216:219], v119 offset:25664
	v_mfma_f32_16x16x32_bf16 v[2:5], v[220:223], v[208:211], v[2:5]
	ds_read_b128 v[220:223], v119 offset:28224
	ds_read_b128 v[208:211], v205 offset:41024
	ds_read_b128 v[224:227], v205 offset:48704
	s_waitcnt lgkmcnt(1)
	v_mfma_f32_16x16x32_bf16 v[6:9], v[90:93], v[208:211], v[6:9]
	v_mfma_f32_16x16x32_bf16 v[30:33], v[212:215], v[208:211], v[30:33]
	s_waitcnt vmcnt(7)
	ds_write_b128 v0, v[82:85] offset:0
	v_mfma_f32_16x16x32_bf16 v[38:41], v[216:219], v[208:211], v[38:41]
	v_mfma_f32_16x16x32_bf16 v[42:45], v[220:223], v[208:211], v[42:45]
	ds_read_b128 v[208:211], v205 offset:43584
	s_waitcnt lgkmcnt(0)
	v_mfma_f32_16x16x32_bf16 v[46:49], v[90:93], v[208:211], v[46:49]
	v_mfma_f32_16x16x32_bf16 v[26:29], v[212:215], v[208:211], v[26:29]
	s_waitcnt vmcnt(6)
	ds_write_b128 v0, v[86:89] offset:10240
	v_mfma_f32_16x16x32_bf16 v[14:17], v[216:219], v[208:211], v[14:17]
	v_mfma_f32_16x16x32_bf16 v[10:13], v[220:223], v[208:211], v[10:13]
	ds_read_b128 v[208:211], v205 offset:46144
	s_waitcnt lgkmcnt(0)
	v_mfma_f32_16x16x32_bf16 v[34:37], v[90:93], v[208:211], v[34:37]
	v_mfma_f32_16x16x32_bf16 v[22:25], v[212:215], v[208:211], v[22:25]
	v_mfma_f32_16x16x32_bf16 v[18:21], v[216:219], v[208:211], v[18:21]
	v_mfma_f32_16x16x32_bf16 v[62:65], v[220:223], v[208:211], v[62:65]
	v_mfma_f32_16x16x32_bf16 v[58:61], v[90:93], v[224:227], v[58:61]
	s_waitcnt lgkmcnt(0)
	v_mfma_f32_16x16x32_bf16 v[54:57], v[212:215], v[224:227], v[54:57]
	s_barrier
	v_mfma_f32_16x16x32_bf16 v[50:53], v[216:219], v[224:227], v[50:53]
	v_mfma_f32_16x16x32_bf16 v[2:5], v[220:223], v[224:227], v[2:5]
	global_load_dwordx4 v[66:69], v190, s[80:81] offset:768
	global_load_dwordx4 v[70:73], v191, s[80:81] offset:768
	global_load_dwordx4 v[74:77], v190, s[86:87] offset:768
	global_load_dwordx4 v[78:81], v191, s[86:87] offset:768
	global_load_dwordx4 v[82:85], v188, s[96:97] offset:768
	global_load_dwordx4 v[86:89], v188, s[98:99] offset:768
	ds_read_b128 v[90:93], v119 offset:0
	ds_read_b128 v[208:211], v205 offset:0
	ds_read_b128 v[212:215], v119 offset:2560
	ds_read_b128 v[216:219], v119 offset:5120
	ds_read_b128 v[220:223], v119 offset:7680
	s_waitcnt lgkmcnt(3)
	v_mfma_f32_16x16x32_bf16 v[6:9], v[90:93], v[208:211], v[6:9]
	s_waitcnt lgkmcnt(2)
	v_mfma_f32_16x16x32_bf16 v[30:33], v[212:215], v[208:211], v[30:33]
	s_waitcnt vmcnt(11)
	ds_write_b128 v207, v[228:231] offset:0
	s_waitcnt lgkmcnt(2)
	v_mfma_f32_16x16x32_bf16 v[38:41], v[216:219], v[208:211], v[38:41]
	s_waitcnt lgkmcnt(1)
	v_mfma_f32_16x16x32_bf16 v[42:45], v[220:223], v[208:211], v[42:45]
	ds_read_b128 v[208:211], v205 offset:2560
	s_waitcnt lgkmcnt(0)
	v_mfma_f32_16x16x32_bf16 v[46:49], v[90:93], v[208:211], v[46:49]
	v_mfma_f32_16x16x32_bf16 v[26:29], v[212:215], v[208:211], v[26:29]
	s_waitcnt vmcnt(10)
	ds_write_b128 v207, v[232:235] offset:10240
	v_mfma_f32_16x16x32_bf16 v[14:17], v[216:219], v[208:211], v[14:17]
	v_mfma_f32_16x16x32_bf16 v[10:13], v[220:223], v[208:211], v[10:13]
	ds_read_b128 v[208:211], v205 offset:5120
	s_waitcnt lgkmcnt(0)
	v_mfma_f32_16x16x32_bf16 v[34:37], v[90:93], v[208:211], v[34:37]
	v_mfma_f32_16x16x32_bf16 v[22:25], v[212:215], v[208:211], v[22:25]
	s_waitcnt vmcnt(9)
	ds_write_b128 v207, v[236:239] offset:20480
	v_mfma_f32_16x16x32_bf16 v[18:21], v[216:219], v[208:211], v[18:21]
	v_mfma_f32_16x16x32_bf16 v[62:65], v[220:223], v[208:211], v[62:65]
	ds_read_b128 v[208:211], v205 offset:7680
	s_waitcnt lgkmcnt(0)
	v_mfma_f32_16x16x32_bf16 v[58:61], v[90:93], v[208:211], v[58:61]
	ds_read_b128 v[90:93], v119 offset:64
	v_mfma_f32_16x16x32_bf16 v[54:57], v[212:215], v[208:211], v[54:57]
	s_waitcnt vmcnt(8)
	ds_write_b128 v207, v[240:243] offset:30720
	ds_read_b128 v[212:215], v119 offset:2624
	v_mfma_f32_16x16x32_bf16 v[50:53], v[216:219], v[208:211], v[50:53]
	ds_read_b128 v[216:219], v119 offset:5184
	v_mfma_f32_16x16x32_bf16 v[2:5], v[220:223], v[208:211], v[2:5]
	ds_read_b128 v[220:223], v119 offset:7744
	ds_read_b128 v[208:211], v205 offset:64
	ds_read_b128 v[224:227], v205 offset:7744
	s_waitcnt lgkmcnt(1)
	v_mfma_f32_16x16x32_bf16 v[6:9], v[90:93], v[208:211], v[6:9]
	v_mfma_f32_16x16x32_bf16 v[30:33], v[212:215], v[208:211], v[30:33]
	s_waitcnt vmcnt(7)
	ds_write_b128 v0, v[244:247] offset:20480
	v_mfma_f32_16x16x32_bf16 v[38:41], v[216:219], v[208:211], v[38:41]
	v_mfma_f32_16x16x32_bf16 v[42:45], v[220:223], v[208:211], v[42:45]
	ds_read_b128 v[208:211], v205 offset:2624
	s_waitcnt lgkmcnt(0)
	v_mfma_f32_16x16x32_bf16 v[46:49], v[90:93], v[208:211], v[46:49]
	v_mfma_f32_16x16x32_bf16 v[26:29], v[212:215], v[208:211], v[26:29]
	s_waitcnt vmcnt(6)
	ds_write_b128 v0, v[248:251] offset:30720
	v_mfma_f32_16x16x32_bf16 v[14:17], v[216:219], v[208:211], v[14:17]
	v_mfma_f32_16x16x32_bf16 v[10:13], v[220:223], v[208:211], v[10:13]
	ds_read_b128 v[208:211], v205 offset:5184
	s_waitcnt lgkmcnt(0)
	v_mfma_f32_16x16x32_bf16 v[34:37], v[90:93], v[208:211], v[34:37]
	v_mfma_f32_16x16x32_bf16 v[22:25], v[212:215], v[208:211], v[22:25]
	v_mfma_f32_16x16x32_bf16 v[18:21], v[216:219], v[208:211], v[18:21]
	v_mfma_f32_16x16x32_bf16 v[62:65], v[220:223], v[208:211], v[62:65]
	v_mfma_f32_16x16x32_bf16 v[58:61], v[90:93], v[224:227], v[58:61]
	s_waitcnt lgkmcnt(0)
	v_mfma_f32_16x16x32_bf16 v[54:57], v[212:215], v[224:227], v[54:57]
	s_barrier
	v_mfma_f32_16x16x32_bf16 v[50:53], v[216:219], v[224:227], v[50:53]
	v_mfma_f32_16x16x32_bf16 v[2:5], v[220:223], v[224:227], v[2:5]
	global_load_dwordx4 v[228:231], v190, s[80:81] offset:896
	global_load_dwordx4 v[232:235], v191, s[80:81] offset:896
	global_load_dwordx4 v[236:239], v190, s[86:87] offset:896
	global_load_dwordx4 v[240:243], v191, s[86:87] offset:896
	global_load_dwordx4 v[244:247], v188, s[96:97] offset:896
	global_load_dwordx4 v[248:251], v188, s[98:99] offset:896
	ds_read_b128 v[90:93], v119 offset:20480
	ds_read_b128 v[208:211], v205 offset:40960
	ds_read_b128 v[212:215], v119 offset:23040
	ds_read_b128 v[216:219], v119 offset:25600
	ds_read_b128 v[220:223], v119 offset:28160
	s_waitcnt lgkmcnt(3)
	v_mfma_f32_16x16x32_bf16 v[6:9], v[90:93], v[208:211], v[6:9]
	s_waitcnt lgkmcnt(2)
	v_mfma_f32_16x16x32_bf16 v[30:33], v[212:215], v[208:211], v[30:33]
	s_waitcnt vmcnt(11)
	ds_write_b128 v206, v[66:69] offset:0
	s_waitcnt lgkmcnt(2)
	v_mfma_f32_16x16x32_bf16 v[38:41], v[216:219], v[208:211], v[38:41]
	s_waitcnt lgkmcnt(1)
	v_mfma_f32_16x16x32_bf16 v[42:45], v[220:223], v[208:211], v[42:45]
	ds_read_b128 v[208:211], v205 offset:43520
	s_waitcnt lgkmcnt(0)
	v_mfma_f32_16x16x32_bf16 v[46:49], v[90:93], v[208:211], v[46:49]
	v_mfma_f32_16x16x32_bf16 v[26:29], v[212:215], v[208:211], v[26:29]
	s_waitcnt vmcnt(10)
	ds_write_b128 v206, v[70:73] offset:10240
	v_mfma_f32_16x16x32_bf16 v[14:17], v[216:219], v[208:211], v[14:17]
	v_mfma_f32_16x16x32_bf16 v[10:13], v[220:223], v[208:211], v[10:13]
	ds_read_b128 v[208:211], v205 offset:46080
	s_waitcnt lgkmcnt(0)
	v_mfma_f32_16x16x32_bf16 v[34:37], v[90:93], v[208:211], v[34:37]
	v_mfma_f32_16x16x32_bf16 v[22:25], v[212:215], v[208:211], v[22:25]
	s_waitcnt vmcnt(9)
	ds_write_b128 v206, v[74:77] offset:20480
	v_mfma_f32_16x16x32_bf16 v[18:21], v[216:219], v[208:211], v[18:21]
	v_mfma_f32_16x16x32_bf16 v[62:65], v[220:223], v[208:211], v[62:65]
	ds_read_b128 v[208:211], v205 offset:48640
	s_waitcnt lgkmcnt(0)
	v_mfma_f32_16x16x32_bf16 v[58:61], v[90:93], v[208:211], v[58:61]
	ds_read_b128 v[90:93], v119 offset:20544
	v_mfma_f32_16x16x32_bf16 v[54:57], v[212:215], v[208:211], v[54:57]
	s_waitcnt vmcnt(8)
	ds_write_b128 v206, v[78:81] offset:30720
	ds_read_b128 v[212:215], v119 offset:23104
	v_mfma_f32_16x16x32_bf16 v[50:53], v[216:219], v[208:211], v[50:53]
	ds_read_b128 v[216:219], v119 offset:25664
	v_mfma_f32_16x16x32_bf16 v[2:5], v[220:223], v[208:211], v[2:5]
	ds_read_b128 v[220:223], v119 offset:28224
	ds_read_b128 v[208:211], v205 offset:41024
	ds_read_b128 v[224:227], v205 offset:48704
	s_waitcnt lgkmcnt(1)
	v_mfma_f32_16x16x32_bf16 v[6:9], v[90:93], v[208:211], v[6:9]
	v_mfma_f32_16x16x32_bf16 v[30:33], v[212:215], v[208:211], v[30:33]
	s_waitcnt vmcnt(7)
	ds_write_b128 v0, v[82:85] offset:0
	v_mfma_f32_16x16x32_bf16 v[38:41], v[216:219], v[208:211], v[38:41]
	v_mfma_f32_16x16x32_bf16 v[42:45], v[220:223], v[208:211], v[42:45]
	ds_read_b128 v[208:211], v205 offset:43584
	s_waitcnt lgkmcnt(0)
	v_mfma_f32_16x16x32_bf16 v[46:49], v[90:93], v[208:211], v[46:49]
	v_mfma_f32_16x16x32_bf16 v[26:29], v[212:215], v[208:211], v[26:29]
	s_waitcnt vmcnt(6)
	ds_write_b128 v0, v[86:89] offset:10240
	v_mfma_f32_16x16x32_bf16 v[14:17], v[216:219], v[208:211], v[14:17]
	v_mfma_f32_16x16x32_bf16 v[10:13], v[220:223], v[208:211], v[10:13]
	ds_read_b128 v[208:211], v205 offset:46144
	s_waitcnt lgkmcnt(0)
	v_mfma_f32_16x16x32_bf16 v[34:37], v[90:93], v[208:211], v[34:37]
	v_mfma_f32_16x16x32_bf16 v[22:25], v[212:215], v[208:211], v[22:25]
	v_mfma_f32_16x16x32_bf16 v[18:21], v[216:219], v[208:211], v[18:21]
	v_mfma_f32_16x16x32_bf16 v[62:65], v[220:223], v[208:211], v[62:65]
	v_mfma_f32_16x16x32_bf16 v[58:61], v[90:93], v[224:227], v[58:61]
	s_waitcnt lgkmcnt(0)
	v_mfma_f32_16x16x32_bf16 v[54:57], v[212:215], v[224:227], v[54:57]
	s_barrier
	v_mfma_f32_16x16x32_bf16 v[50:53], v[216:219], v[224:227], v[50:53]
	v_mfma_f32_16x16x32_bf16 v[2:5], v[220:223], v[224:227], v[2:5]
	ds_read_b128 v[90:93], v119 offset:0
	ds_read_b128 v[208:211], v205 offset:0
	ds_read_b128 v[212:215], v119 offset:2560
	ds_read_b128 v[216:219], v119 offset:5120
	ds_read_b128 v[220:223], v119 offset:7680
	s_waitcnt lgkmcnt(3)
	v_mfma_f32_16x16x32_bf16 v[6:9], v[90:93], v[208:211], v[6:9]
	s_waitcnt lgkmcnt(2)
	v_mfma_f32_16x16x32_bf16 v[30:33], v[212:215], v[208:211], v[30:33]
	s_waitcnt vmcnt(5)
	ds_write_b128 v207, v[228:231] offset:0
	s_waitcnt lgkmcnt(2)
	v_mfma_f32_16x16x32_bf16 v[38:41], v[216:219], v[208:211], v[38:41]
	s_waitcnt lgkmcnt(1)
	v_mfma_f32_16x16x32_bf16 v[42:45], v[220:223], v[208:211], v[42:45]
	ds_read_b128 v[208:211], v205 offset:2560
	s_waitcnt lgkmcnt(0)
	v_mfma_f32_16x16x32_bf16 v[46:49], v[90:93], v[208:211], v[46:49]
	v_mfma_f32_16x16x32_bf16 v[26:29], v[212:215], v[208:211], v[26:29]
	s_waitcnt vmcnt(4)
	ds_write_b128 v207, v[232:235] offset:10240
	v_mfma_f32_16x16x32_bf16 v[14:17], v[216:219], v[208:211], v[14:17]
	v_mfma_f32_16x16x32_bf16 v[10:13], v[220:223], v[208:211], v[10:13]
	ds_read_b128 v[208:211], v205 offset:5120
	s_waitcnt lgkmcnt(0)
	v_mfma_f32_16x16x32_bf16 v[34:37], v[90:93], v[208:211], v[34:37]
	v_mfma_f32_16x16x32_bf16 v[22:25], v[212:215], v[208:211], v[22:25]
	s_waitcnt vmcnt(3)
	ds_write_b128 v207, v[236:239] offset:20480
	v_mfma_f32_16x16x32_bf16 v[18:21], v[216:219], v[208:211], v[18:21]
	v_mfma_f32_16x16x32_bf16 v[62:65], v[220:223], v[208:211], v[62:65]
	ds_read_b128 v[208:211], v205 offset:7680
	s_waitcnt lgkmcnt(0)
	v_mfma_f32_16x16x32_bf16 v[58:61], v[90:93], v[208:211], v[58:61]
	ds_read_b128 v[90:93], v119 offset:64
	v_mfma_f32_16x16x32_bf16 v[54:57], v[212:215], v[208:211], v[54:57]
	s_waitcnt vmcnt(2)
	ds_write_b128 v207, v[240:243] offset:30720
	ds_read_b128 v[212:215], v119 offset:2624
	v_mfma_f32_16x16x32_bf16 v[50:53], v[216:219], v[208:211], v[50:53]
	ds_read_b128 v[216:219], v119 offset:5184
	v_mfma_f32_16x16x32_bf16 v[2:5], v[220:223], v[208:211], v[2:5]
	ds_read_b128 v[220:223], v119 offset:7744
	ds_read_b128 v[208:211], v205 offset:64
	ds_read_b128 v[224:227], v205 offset:7744
	s_waitcnt lgkmcnt(1)
	v_mfma_f32_16x16x32_bf16 v[6:9], v[90:93], v[208:211], v[6:9]
	v_mfma_f32_16x16x32_bf16 v[30:33], v[212:215], v[208:211], v[30:33]
	s_waitcnt vmcnt(1)
	ds_write_b128 v0, v[244:247] offset:20480
	v_mfma_f32_16x16x32_bf16 v[38:41], v[216:219], v[208:211], v[38:41]
	v_mfma_f32_16x16x32_bf16 v[42:45], v[220:223], v[208:211], v[42:45]
	ds_read_b128 v[208:211], v205 offset:2624
	s_waitcnt lgkmcnt(0)
	v_mfma_f32_16x16x32_bf16 v[46:49], v[90:93], v[208:211], v[46:49]
	v_mfma_f32_16x16x32_bf16 v[26:29], v[212:215], v[208:211], v[26:29]
	s_waitcnt vmcnt(0)
	ds_write_b128 v0, v[248:251] offset:30720
	v_mfma_f32_16x16x32_bf16 v[14:17], v[216:219], v[208:211], v[14:17]
	v_mfma_f32_16x16x32_bf16 v[10:13], v[220:223], v[208:211], v[10:13]
	ds_read_b128 v[208:211], v205 offset:5184
	s_waitcnt lgkmcnt(0)
	v_mfma_f32_16x16x32_bf16 v[34:37], v[90:93], v[208:211], v[34:37]
	v_mfma_f32_16x16x32_bf16 v[22:25], v[212:215], v[208:211], v[22:25]
	v_mfma_f32_16x16x32_bf16 v[18:21], v[216:219], v[208:211], v[18:21]
	v_mfma_f32_16x16x32_bf16 v[62:65], v[220:223], v[208:211], v[62:65]
	v_mfma_f32_16x16x32_bf16 v[58:61], v[90:93], v[224:227], v[58:61]
	s_waitcnt lgkmcnt(0)
	v_mfma_f32_16x16x32_bf16 v[54:57], v[212:215], v[224:227], v[54:57]
	s_barrier
	v_mfma_f32_16x16x32_bf16 v[50:53], v[216:219], v[224:227], v[50:53]
	v_mfma_f32_16x16x32_bf16 v[2:5], v[220:223], v[224:227], v[2:5]
	ds_read_b128 v[66:69], v205 offset:40960
	ds_read_b128 v[70:73], v205 offset:43520
	ds_read_b128 v[74:77], v205 offset:46080
	ds_read_b128 v[78:81], v205 offset:48640
	ds_read_b128 v[82:85], v119 offset:20480
	ds_read_b128 v[86:89], v119 offset:23040
	ds_read_b128 v[90:93], v119 offset:25600
	ds_read_b128 v[188:191], v119 offset:28160
	s_lshl_b32 s8, s66, 10
	s_waitcnt lgkmcnt(3)
	v_mfma_f32_16x16x32_bf16 v[6:9], v[82:85], v[66:69], v[6:9]
	s_add_i32 s66, s66, 1
	s_add_u32 s6, s6, 0x100000
	s_addc_u32 s7, s7, 0
	s_waitcnt lgkmcnt(2)
	v_mfma_f32_16x16x32_bf16 v[30:33], v[86:89], v[66:69], v[30:33]
	s_cmp_eq_u32 s66, 4
	s_waitcnt lgkmcnt(1)
	v_mfma_f32_16x16x32_bf16 v[38:41], v[90:93], v[66:69], v[38:41]
	s_waitcnt lgkmcnt(0)
	v_mfma_f32_16x16x32_bf16 v[42:45], v[188:191], v[66:69], v[42:45]
	v_mfma_f32_16x16x32_bf16 v[46:49], v[82:85], v[70:73], v[46:49]
	v_mfma_f32_16x16x32_bf16 v[26:29], v[86:89], v[70:73], v[26:29]
	v_mfma_f32_16x16x32_bf16 v[14:17], v[90:93], v[70:73], v[14:17]
	v_mfma_f32_16x16x32_bf16 v[10:13], v[188:191], v[70:73], v[10:13]
	v_mfma_f32_16x16x32_bf16 v[66:69], v[82:85], v[74:77], v[34:37]
	v_mfma_f32_16x16x32_bf16 v[22:25], v[86:89], v[74:77], v[22:25]
	v_mfma_f32_16x16x32_bf16 v[18:21], v[90:93], v[74:77], v[18:21]
	v_mfma_f32_16x16x32_bf16 v[62:65], v[188:191], v[74:77], v[62:65]
	v_mfma_f32_16x16x32_bf16 v[58:61], v[82:85], v[78:81], v[58:61]
	v_mfma_f32_16x16x32_bf16 v[54:57], v[86:89], v[78:81], v[54:57]
	v_mfma_f32_16x16x32_bf16 v[70:73], v[90:93], v[78:81], v[50:53]
	v_mfma_f32_16x16x32_bf16 v[2:5], v[188:191], v[78:81], v[2:5]
	ds_read_b128 v[34:37], v205 offset:41024
	ds_read_b128 v[74:77], v205 offset:43584
	ds_read_b128 v[78:81], v205 offset:46144
	ds_read_b128 v[82:85], v205 offset:48704
	ds_read_b128 v[86:89], v119 offset:20544
	ds_read_b128 v[90:93], v119 offset:23104
	ds_read_b128 v[188:191], v119 offset:25664
	ds_read_b128 v[206:209], v119 offset:28224
	s_waitcnt lgkmcnt(0)
	s_barrier
	v_mfma_f32_16x16x32_bf16 v[210:213], v[86:89], v[34:37], v[6:9]
	v_mfma_f32_16x16x32_bf16 v[214:217], v[90:93], v[34:37], v[30:33]
	v_mfma_f32_16x16x32_bf16 v[218:221], v[188:191], v[34:37], v[38:41]
	v_mfma_f32_16x16x32_bf16 v[50:53], v[206:209], v[34:37], v[42:45]
	v_mfma_f32_16x16x32_bf16 v[34:37], v[206:209], v[74:77], v[10:13]
	v_mfma_f32_16x16x32_bf16 v[10:13], v[90:93], v[82:85], v[54:57]
	s_nop 2
	v_lshl_add_u64 v[54:55], v[128:129], 0, s[8:9]
	global_load_dwordx2 v[56:57], v[54:55], off
	v_mfma_f32_16x16x32_bf16 v[38:41], v[188:191], v[74:77], v[14:17]
	global_load_dwordx2 v[54:55], v[54:55], off offset:32
	v_mfma_f32_16x16x32_bf16 v[14:17], v[86:89], v[82:85], v[58:61]
	v_mfma_f32_16x16x32_bf16 v[46:49], v[86:89], v[74:77], v[46:49]
	s_waitcnt vmcnt(1)
	s_nop 0
	v_cvt_f32_ubyte1_e32 v59, v56
	v_cvt_f32_ubyte0_e32 v58, v56
	v_pk_mul_f32 v[58:59], v[58:59], s[34:35] op_sel_hi:[1,0]
	v_mfma_f32_16x16x32_bf16 v[42:45], v[90:93], v[74:77], v[26:29]
	v_fma_f32 v184, v210, v58, v184
	v_fma_f32 v185, v211, v59, v185
	v_cvt_f32_ubyte3_e32 v59, v56
	v_cvt_f32_ubyte2_e32 v58, v56
	v_pk_mul_f32 v[58:59], v[58:59], s[34:35] op_sel_hi:[1,0]
	v_mfma_f32_16x16x32_bf16 v[30:33], v[86:89], v[78:81], v[66:69]
	v_fma_f32 v186, v212, v58, v186
	v_fma_f32 v187, v213, v59, v187
	v_cvt_f32_ubyte1_e32 v59, v57
	v_cvt_f32_ubyte0_e32 v58, v57
	v_pk_mul_f32 v[58:59], v[58:59], s[34:35] op_sel_hi:[1,0]
	v_mfma_f32_16x16x32_bf16 v[26:29], v[90:93], v[78:81], v[22:25]
	v_fma_f32 v180, v214, v58, v180
	v_fma_f32 v181, v215, v59, v181
	v_cvt_f32_ubyte3_e32 v59, v57
	v_cvt_f32_ubyte2_e32 v58, v57
	v_pk_mul_f32 v[56:57], v[58:59], s[34:35] op_sel_hi:[1,0]
	v_mfma_f32_16x16x32_bf16 v[22:25], v[188:191], v[78:81], v[18:21]
	v_fma_f32 v182, v216, v56, v182
	v_fma_f32 v183, v217, v57, v183
	s_waitcnt vmcnt(0)
	v_cvt_f32_ubyte1_e32 v57, v54
	v_cvt_f32_ubyte0_e32 v56, v54
	v_pk_mul_f32 v[56:57], v[56:57], s[34:35] op_sel_hi:[1,0]
	v_mfma_f32_16x16x32_bf16 v[18:21], v[206:209], v[78:81], v[62:65]
	v_fma_f32 v176, v218, v56, v176
	v_fma_f32 v177, v219, v57, v177
	v_cvt_f32_ubyte3_e32 v57, v54
	v_cvt_f32_ubyte2_e32 v56, v54
	v_pk_mul_f32 v[56:57], v[56:57], s[34:35] op_sel_hi:[1,0]
	v_mfma_f32_16x16x32_bf16 v[6:9], v[188:191], v[82:85], v[70:73]
	v_fma_f32 v178, v220, v56, v178
	v_fma_f32 v179, v221, v57, v179
	v_cvt_f32_ubyte1_e32 v57, v55
	v_cvt_f32_ubyte0_e32 v56, v55
	v_pk_mul_f32 v[56:57], v[56:57], s[34:35] op_sel_hi:[1,0]
	v_mfma_f32_16x16x32_bf16 v[2:5], v[206:209], v[82:85], v[2:5]
	v_fma_f32 v172, v50, v56, v172
	v_fma_f32 v173, v51, v57, v173
	v_cvt_f32_ubyte3_e32 v51, v55
	v_cvt_f32_ubyte2_e32 v50, v55
	v_pk_mul_f32 v[50:51], v[50:51], s[34:35] op_sel_hi:[1,0]
	s_nop 0
	v_pk_fma_f32 v[174:175], v[52:53], v[50:51], v[174:175]
	v_lshl_add_u64 v[50:51], v[132:133], 0, s[8:9]
	global_load_dwordx2 v[52:53], v[50:51], off
	s_waitcnt vmcnt(0)
	v_cvt_f32_ubyte1_e32 v55, v52
	v_cvt_f32_ubyte0_e32 v54, v52
	v_pk_mul_f32 v[54:55], v[54:55], s[34:35] op_sel_hi:[1,0]
	s_nop 0
	v_pk_fma_f32 v[168:169], v[46:47], v[54:55], v[168:169]
	v_cvt_f32_ubyte3_e32 v47, v52
	v_cvt_f32_ubyte2_e32 v46, v52
	v_pk_mul_f32 v[46:47], v[46:47], s[34:35] op_sel_hi:[1,0]
	s_nop 0
	v_pk_fma_f32 v[170:171], v[48:49], v[46:47], v[170:171]
	v_cvt_f32_ubyte1_e32 v47, v53
	v_cvt_f32_ubyte0_e32 v46, v53
	v_pk_mul_f32 v[46:47], v[46:47], s[34:35] op_sel_hi:[1,0]
	s_nop 0
	v_pk_fma_f32 v[164:165], v[42:43], v[46:47], v[164:165]
	v_cvt_f32_ubyte3_e32 v43, v53
	v_cvt_f32_ubyte2_e32 v42, v53
	v_pk_mul_f32 v[42:43], v[42:43], s[34:35] op_sel_hi:[1,0]
	s_nop 0
	v_pk_fma_f32 v[166:167], v[44:45], v[42:43], v[166:167]
	global_load_dwordx2 v[42:43], v[50:51], off offset:32
	s_waitcnt vmcnt(0)
	v_cvt_f32_ubyte1_e32 v45, v42
	v_cvt_f32_ubyte0_e32 v44, v42
	v_pk_mul_f32 v[44:45], v[44:45], s[34:35] op_sel_hi:[1,0]
	s_nop 0
	v_pk_fma_f32 v[160:161], v[38:39], v[44:45], v[160:161]
	v_cvt_f32_ubyte3_e32 v39, v42
	v_cvt_f32_ubyte2_e32 v38, v42
	v_pk_mul_f32 v[38:39], v[38:39], s[34:35] op_sel_hi:[1,0]
	s_nop 0
	v_pk_fma_f32 v[162:163], v[40:41], v[38:39], v[162:163]
	v_cvt_f32_ubyte1_e32 v39, v43
	v_cvt_f32_ubyte0_e32 v38, v43
	v_pk_mul_f32 v[38:39], v[38:39], s[34:35] op_sel_hi:[1,0]
	s_nop 0
	v_pk_fma_f32 v[156:157], v[34:35], v[38:39], v[156:157]
	v_cvt_f32_ubyte3_e32 v35, v43
	v_cvt_f32_ubyte2_e32 v34, v43
	v_pk_mul_f32 v[34:35], v[34:35], s[34:35] op_sel_hi:[1,0]
	s_nop 0
	v_pk_fma_f32 v[158:159], v[36:37], v[34:35], v[158:159]
	v_lshl_add_u64 v[34:35], v[152:153], 0, s[8:9]
	global_load_dwordx2 v[36:37], v[34:35], off
	s_waitcnt vmcnt(0)
	v_cvt_f32_ubyte1_e32 v39, v36
	v_cvt_f32_ubyte0_e32 v38, v36
	v_pk_mul_f32 v[38:39], v[38:39], s[34:35] op_sel_hi:[1,0]
	s_nop 0
	v_pk_fma_f32 v[136:137], v[30:31], v[38:39], v[136:137]
	v_cvt_f32_ubyte3_e32 v31, v36
	v_cvt_f32_ubyte2_e32 v30, v36
	v_pk_mul_f32 v[30:31], v[30:31], s[34:35] op_sel_hi:[1,0]
	s_nop 0
	v_pk_fma_f32 v[150:151], v[32:33], v[30:31], v[150:151]
	v_cvt_f32_ubyte1_e32 v31, v37
	v_cvt_f32_ubyte0_e32 v30, v37
	v_pk_mul_f32 v[30:31], v[30:31], s[34:35] op_sel_hi:[1,0]
	s_nop 0
	v_pk_fma_f32 v[130:131], v[26:27], v[30:31], v[130:131]
	v_cvt_f32_ubyte3_e32 v27, v37
	v_cvt_f32_ubyte2_e32 v26, v37
	v_pk_mul_f32 v[26:27], v[26:27], s[34:35] op_sel_hi:[1,0]
	s_nop 0
	v_pk_fma_f32 v[134:135], v[28:29], v[26:27], v[134:135]
	global_load_dwordx2 v[26:27], v[34:35], off offset:32
	s_waitcnt vmcnt(0)
	v_cvt_f32_ubyte1_e32 v29, v26
	v_cvt_f32_ubyte0_e32 v28, v26
	v_pk_mul_f32 v[28:29], v[28:29], s[34:35] op_sel_hi:[1,0]
	s_nop 0
	v_pk_fma_f32 v[124:125], v[22:23], v[28:29], v[124:125]
	v_cvt_f32_ubyte3_e32 v23, v26
	v_cvt_f32_ubyte2_e32 v22, v26
	v_pk_mul_f32 v[22:23], v[22:23], s[34:35] op_sel_hi:[1,0]
	s_nop 0
	v_pk_fma_f32 v[126:127], v[24:25], v[22:23], v[126:127]
	v_cvt_f32_ubyte1_e32 v23, v27
	v_cvt_f32_ubyte0_e32 v22, v27
	v_pk_mul_f32 v[22:23], v[22:23], s[34:35] op_sel_hi:[1,0]
	s_nop 0
	v_pk_fma_f32 v[120:121], v[18:19], v[22:23], v[120:121]
	v_cvt_f32_ubyte3_e32 v19, v27
	v_cvt_f32_ubyte2_e32 v18, v27
	v_pk_mul_f32 v[18:19], v[18:19], s[34:35] op_sel_hi:[1,0]
	s_nop 0
	v_pk_fma_f32 v[122:123], v[20:21], v[18:19], v[122:123]
	v_lshl_add_u64 v[18:19], v[154:155], 0, s[8:9]
	global_load_dwordx2 v[20:21], v[18:19], off
	s_waitcnt vmcnt(0)
	v_cvt_f32_ubyte1_e32 v23, v20
	v_cvt_f32_ubyte0_e32 v22, v20
	v_pk_mul_f32 v[22:23], v[22:23], s[34:35] op_sel_hi:[1,0]
	s_nop 0
	v_pk_fma_f32 v[114:115], v[14:15], v[22:23], v[114:115]
	v_cvt_f32_ubyte3_e32 v15, v20
	v_cvt_f32_ubyte2_e32 v14, v20
	v_pk_mul_f32 v[14:15], v[14:15], s[34:35] op_sel_hi:[1,0]
	s_nop 0
	v_pk_fma_f32 v[116:117], v[16:17], v[14:15], v[116:117]
	v_cvt_f32_ubyte1_e32 v15, v21
	v_cvt_f32_ubyte0_e32 v14, v21
	v_pk_mul_f32 v[14:15], v[14:15], s[34:35] op_sel_hi:[1,0]
	s_nop 0
	v_pk_fma_f32 v[106:107], v[10:11], v[14:15], v[106:107]
	v_cvt_f32_ubyte3_e32 v11, v21
	v_cvt_f32_ubyte2_e32 v10, v21
	v_pk_mul_f32 v[10:11], v[10:11], s[34:35] op_sel_hi:[1,0]
	s_nop 0
	v_pk_fma_f32 v[108:109], v[12:13], v[10:11], v[108:109]
	global_load_dwordx2 v[10:11], v[18:19], off offset:32
	s_waitcnt vmcnt(0)
	v_cvt_f32_ubyte1_e32 v13, v10
	v_cvt_f32_ubyte0_e32 v12, v10
	v_pk_mul_f32 v[12:13], v[12:13], s[34:35] op_sel_hi:[1,0]
	s_nop 0
	v_pk_fma_f32 v[100:101], v[6:7], v[12:13], v[100:101]
	v_cvt_f32_ubyte3_e32 v7, v10
	v_cvt_f32_ubyte2_e32 v6, v10
	v_pk_mul_f32 v[6:7], v[6:7], s[34:35] op_sel_hi:[1,0]
	s_nop 0
	v_pk_fma_f32 v[102:103], v[8:9], v[6:7], v[102:103]
	v_cvt_f32_ubyte1_e32 v7, v11
	v_cvt_f32_ubyte0_e32 v6, v11
	v_pk_mul_f32 v[6:7], v[6:7], s[34:35] op_sel_hi:[1,0]
	s_nop 0
	v_pk_fma_f32 v[96:97], v[2:3], v[6:7], v[96:97]
	v_cvt_f32_ubyte3_e32 v3, v11
	v_cvt_f32_ubyte2_e32 v2, v11
	v_pk_mul_f32 v[2:3], v[2:3], s[34:35] op_sel_hi:[1,0]
	s_nop 0
	v_pk_fma_f32 v[98:99], v[4:5], v[2:3], v[98:99]
	s_cbranch_scc0 .LBB0_1004
	v_lshlrev_b32_e32 v0, 1, v118
	v_lshl_add_u64 v[6:7], s[4:5], 0, v[0:1]
	v_lshlrev_b64 v[2:3], 11, v[112:113]
	v_lshl_add_u64 v[8:9], v[6:7], 0, v[2:3]
	v_cvt_pk_bf16_f32 v2, v184, v185
	v_cvt_pk_bf16_f32 v3, v186, v187
	v_cvt_pk_bf16_f32 v4, v180, v181
	v_cvt_pk_bf16_f32 v5, v182, v183
	global_store_dwordx4 v[8:9], v[2:5], off
	v_readlane_b32 s46, v254, 29
	s_mov_b32 s38, 0
	v_cvt_pk_bf16_f32 v2, v176, v177
	v_cvt_pk_bf16_f32 v3, v178, v179
	v_cvt_pk_bf16_f32 v4, v172, v173
	v_cvt_pk_bf16_f32 v5, v174, v175
	global_store_dwordx4 v[8:9], v[2:5], off offset:64
	v_readlane_b32 s47, v254, 30
	s_nop 0
	v_lshlrev_b64 v[2:3], 11, v[110:111]
	v_lshl_add_u64 v[8:9], v[6:7], 0, v[2:3]
	v_cvt_pk_bf16_f32 v2, v168, v169
	v_cvt_pk_bf16_f32 v3, v170, v171
	v_cvt_pk_bf16_f32 v4, v164, v165
	v_cvt_pk_bf16_f32 v5, v166, v167
	global_store_dwordx4 v[8:9], v[2:5], off
	s_nop 1
	v_cvt_pk_bf16_f32 v2, v160, v161
	v_cvt_pk_bf16_f32 v3, v162, v163
	v_cvt_pk_bf16_f32 v4, v156, v157
	v_cvt_pk_bf16_f32 v5, v158, v159
	global_store_dwordx4 v[8:9], v[2:5], off offset:64
	s_nop 1
	v_lshlrev_b64 v[2:3], 11, v[104:105]
	v_lshl_add_u64 v[8:9], v[6:7], 0, v[2:3]
	v_cvt_pk_bf16_f32 v2, v136, v137
	v_cvt_pk_bf16_f32 v3, v150, v151
	v_cvt_pk_bf16_f32 v4, v130, v131
	v_cvt_pk_bf16_f32 v5, v134, v135
	global_store_dwordx4 v[8:9], v[2:5], off
	s_nop 1
	v_cvt_pk_bf16_f32 v2, v124, v125
	v_cvt_pk_bf16_f32 v3, v126, v127
	v_cvt_pk_bf16_f32 v4, v120, v121
	v_cvt_pk_bf16_f32 v5, v122, v123
	global_store_dwordx4 v[8:9], v[2:5], off offset:64
	s_nop 1
	v_lshlrev_b64 v[2:3], 11, v[94:95]
	v_lshl_add_u64 v[6:7], v[6:7], 0, v[2:3]
	v_cvt_pk_bf16_f32 v2, v114, v115
	v_cvt_pk_bf16_f32 v3, v116, v117
	v_cvt_pk_bf16_f32 v4, v106, v107
	v_cvt_pk_bf16_f32 v5, v108, v109
	global_store_dwordx4 v[6:7], v[2:5], off
	s_nop 1
	v_cvt_pk_bf16_f32 v2, v100, v101
	v_cvt_pk_bf16_f32 v3, v102, v103
	v_cvt_pk_bf16_f32 v4, v96, v97
	v_cvt_pk_bf16_f32 v5, v98, v99
	global_store_dwordx4 v[6:7], v[2:5], off offset:64
